# nt hint also on residual (P5/P7), merge (P4d) and mixer-A output stores
# baseline (speedup 1.0000x reference)
.LBB0_405:
	s_or_b64 exec, exec, s[4:5]
	s_waitcnt lgkmcnt(0)
	v_lshlrev_b32_e32 v129, 2, v134
	global_load_dword v132, v129, s[0:1]
	global_load_dword v131, v129, s[0:1] offset:128
	global_load_dword v130, v129, s[0:1] offset:256
	s_nop 0
	global_load_dword v129, v129, s[0:1] offset:384
	v_ashrrev_i32_e32 v135, 3, v128
	v_and_b32_e32 v139, -4, v135
	v_mov_b32_e32 v133, v200
	v_lshl_add_u32 v143, v134, 1, s48
	v_lshl_add_u32 v134, v139, 2, s59
	ds_read_b96 v[136:138], v134
	ds_read_b96 v[140:142], v134 offset:128
	v_sub_f32_e32 v133, 1.0, v133
	s_add_i32 s6, s6, 1
	s_cmp_eq_u32 s6, 4
	s_waitcnt lgkmcnt(0)
	v_mul_f32_e32 v16, v16, v140
	v_mul_f32_e32 v0, v0, v140
	v_fma_f32 v16, v80, v136, -v16
	v_fma_f32 v0, v64, v136, -v0
	v_mul_f32_e32 v64, v16, v16
	v_mul_f32_e32 v32, v32, v140
	v_fmac_f32_e32 v64, v0, v0
	v_fma_f32 v80, v96, v136, -v32
	v_mul_f32_e32 v32, v48, v140
	v_fmac_f32_e32 v64, v80, v80
	v_fma_f32 v48, v112, v136, -v32
	v_fmac_f32_e32 v64, v48, v48
	ds_swizzle_b32 v32, v64 offset:swizzle(SWAP,1)
	s_waitcnt lgkmcnt(0)
	v_add_f32_e32 v32, v64, v32
	ds_swizzle_b32 v64, v32 offset:swizzle(SWAP,2)
	s_waitcnt lgkmcnt(0)
	v_add_f32_e32 v32, v32, v64
	ds_swizzle_b32 v64, v32 offset:swizzle(SWAP,4)
	s_waitcnt lgkmcnt(0)
	v_add_f32_e32 v32, v32, v64
	ds_swizzle_b32 v64, v32 offset:swizzle(SWAP,8)
	s_waitcnt lgkmcnt(0)
	v_add_f32_e32 v32, v32, v64
	ds_swizzle_b32 v64, v32 offset:swizzle(SWAP,16)
	s_waitcnt lgkmcnt(0)
	v_add_f32_e32 v32, v32, v64
	v_fmamk_f32 v32, v32, 0x3c000000, v204
	v_rsq_f32_e32 v32, v32
	s_nop 0
	v_mul_f32_e32 v64, v133, v32
	v_mul_f32_e32 v0, v0, v64
	v_mul_f32_e32 v16, v16, v64
	v_lshl_add_u32 v32, v139, 8, v143
	v_mul_f32_e32 v80, v80, v64
	v_mul_f32_e32 v48, v48, v64
	s_waitcnt vmcnt(3)
	v_mul_f32_e32 v0, v132, v0
	s_waitcnt vmcnt(2)
	v_mul_f32_e32 v16, v131, v16
	v_cvt_pk_bf16_f32 v0, v0, s0
	s_waitcnt vmcnt(1)
	v_mul_f32_e32 v80, v130, v80
	ds_write_b16 v32, v0
	v_cvt_pk_bf16_f32 v0, v16, s0
	s_waitcnt vmcnt(0)
	v_mul_f32_e32 v48, v129, v48
	ds_write_b16 v32, v0 offset:64
	v_cvt_pk_bf16_f32 v0, v80, s0
	ds_write_b16 v32, v0 offset:128
	v_cvt_pk_bf16_f32 v0, v48, s0
	ds_write_b16 v32, v0 offset:192
	v_mul_f32_e32 v0, v1, v141
	v_mul_f32_e32 v1, v17, v141
	v_fma_f32 v1, v81, v137, -v1
	v_fma_f32 v0, v65, v137, -v0
	v_mul_f32_e32 v16, v1, v1
	v_mul_f32_e32 v17, v33, v141
	v_fmac_f32_e32 v16, v0, v0
	v_fma_f32 v17, v97, v137, -v17
	v_mul_f32_e32 v33, v49, v141
	v_fmac_f32_e32 v16, v17, v17
	v_fma_f32 v33, v113, v137, -v33
	v_fmac_f32_e32 v16, v33, v33
	ds_swizzle_b32 v48, v16 offset:swizzle(SWAP,1)
	s_waitcnt lgkmcnt(0)
	v_add_f32_e32 v16, v16, v48
	ds_swizzle_b32 v48, v16 offset:swizzle(SWAP,2)
	s_waitcnt lgkmcnt(0)
	v_add_f32_e32 v16, v16, v48
	ds_swizzle_b32 v48, v16 offset:swizzle(SWAP,4)
	s_waitcnt lgkmcnt(0)
	v_add_f32_e32 v16, v16, v48
	ds_swizzle_b32 v48, v16 offset:swizzle(SWAP,8)
	s_waitcnt lgkmcnt(0)
	v_add_f32_e32 v16, v16, v48
	ds_swizzle_b32 v48, v16 offset:swizzle(SWAP,16)
	s_waitcnt lgkmcnt(0)
	v_add_f32_e32 v16, v16, v48
	v_fmamk_f32 v16, v16, 0x3c000000, v204
	v_rsq_f32_e32 v16, v16
	s_nop 0
	v_mul_f32_e32 v16, v133, v16
	v_mul_f32_e32 v0, v0, v16
	v_mul_f32_e32 v0, v132, v0
	v_mul_f32_e32 v1, v1, v16
	v_mul_f32_e32 v1, v131, v1
	v_mul_f32_e32 v17, v17, v16
	v_cvt_pk_bf16_f32 v0, v0, s0
	v_mul_f32_e32 v17, v130, v17
	v_mul_f32_e32 v16, v33, v16
	ds_write_b16 v32, v0 offset:256
	v_cvt_pk_bf16_f32 v0, v1, s0
	v_mul_f32_e32 v16, v129, v16
	ds_write_b16 v32, v0 offset:320
	v_cvt_pk_bf16_f32 v0, v17, s0
	ds_write_b16 v32, v0 offset:384
	v_cvt_pk_bf16_f32 v0, v16, s0
	v_mul_f32_e32 v1, v18, v142
	ds_write_b16 v32, v0 offset:448
	v_mul_f32_e32 v0, v2, v142
	v_fma_f32 v1, v82, v138, -v1
	v_fma_f32 v0, v66, v138, -v0
	v_mul_f32_e32 v2, v1, v1
	v_mul_f32_e32 v16, v34, v142
	v_fmac_f32_e32 v2, v0, v0
	v_fma_f32 v16, v98, v138, -v16
	v_mul_f32_e32 v17, v50, v142
	v_fmac_f32_e32 v2, v16, v16
	v_fma_f32 v17, v114, v138, -v17
	v_fmac_f32_e32 v2, v17, v17
	ds_swizzle_b32 v18, v2 offset:swizzle(SWAP,1)
	s_waitcnt lgkmcnt(0)
	v_add_f32_e32 v2, v2, v18
	ds_swizzle_b32 v18, v2 offset:swizzle(SWAP,2)
	s_waitcnt lgkmcnt(0)
	v_add_f32_e32 v2, v2, v18
	ds_swizzle_b32 v18, v2 offset:swizzle(SWAP,4)
	s_waitcnt lgkmcnt(0)
	v_add_f32_e32 v2, v2, v18
	ds_swizzle_b32 v18, v2 offset:swizzle(SWAP,8)
	s_waitcnt lgkmcnt(0)
	v_add_f32_e32 v2, v2, v18
	ds_swizzle_b32 v18, v2 offset:swizzle(SWAP,16)
	s_waitcnt lgkmcnt(0)
	v_add_f32_e32 v2, v2, v18
	v_fmamk_f32 v2, v2, 0x3c000000, v204
	v_rsq_f32_e32 v2, v2
	s_nop 0
	v_mul_f32_e32 v2, v133, v2
	v_mul_f32_e32 v0, v0, v2
	v_mul_f32_e32 v0, v132, v0
	v_mul_f32_e32 v1, v1, v2
	v_mul_f32_e32 v1, v131, v1
	v_mul_f32_e32 v16, v16, v2
	v_cvt_pk_bf16_f32 v0, v0, s0
	v_mul_f32_e32 v16, v130, v16
	v_mul_f32_e32 v2, v17, v2
	ds_write_b16 v32, v0 offset:512
	v_cvt_pk_bf16_f32 v0, v1, s0
	v_mul_f32_e32 v2, v129, v2
	ds_write_b16 v32, v0 offset:576
	v_cvt_pk_bf16_f32 v0, v16, s0
	ds_write_b16 v32, v0 offset:640
	v_cvt_pk_bf16_f32 v0, v2, s0
	v_or_b32_e32 v2, 3, v135
	ds_write_b16 v32, v0 offset:704
	v_lshl_add_u32 v0, v2, 2, s59
	ds_read2_b32 v[0:1], v0 offset1:32
	v_lshl_add_u32 v2, v2, 8, v143
	s_waitcnt lgkmcnt(0)
	v_mul_f32_e32 v16, v19, v1
	v_mul_f32_e32 v3, v3, v1
	v_fma_f32 v16, v83, v0, -v16
	v_fma_f32 v3, v67, v0, -v3
	v_mul_f32_e32 v17, v16, v16
	v_mul_f32_e32 v18, v35, v1
	v_fmac_f32_e32 v17, v3, v3
	v_fma_f32 v18, v99, v0, -v18
	v_mul_f32_e32 v1, v51, v1
	v_fmac_f32_e32 v17, v18, v18
	v_fma_f32 v0, v115, v0, -v1
	v_fmac_f32_e32 v17, v0, v0
	ds_swizzle_b32 v1, v17 offset:swizzle(SWAP,1)
	s_waitcnt lgkmcnt(0)
	v_add_f32_e32 v1, v17, v1
	ds_swizzle_b32 v17, v1 offset:swizzle(SWAP,2)
	s_waitcnt lgkmcnt(0)
	v_add_f32_e32 v1, v1, v17
	ds_swizzle_b32 v17, v1 offset:swizzle(SWAP,4)
	s_waitcnt lgkmcnt(0)
	v_add_f32_e32 v1, v1, v17
	ds_swizzle_b32 v17, v1 offset:swizzle(SWAP,8)
	s_waitcnt lgkmcnt(0)
	v_add_f32_e32 v1, v1, v17
	ds_swizzle_b32 v17, v1 offset:swizzle(SWAP,16)
	s_waitcnt lgkmcnt(0)
	v_add_f32_e32 v1, v1, v17
	v_fmamk_f32 v1, v1, 0x3c000000, v204
	v_rsq_f32_e32 v1, v1
	s_nop 0
	v_mul_f32_e32 v1, v133, v1
	v_mul_f32_e32 v3, v3, v1
	v_mul_f32_e32 v3, v132, v3
	v_mul_f32_e32 v16, v16, v1
	v_mul_f32_e32 v16, v131, v16
	v_mul_f32_e32 v17, v18, v1
	v_mul_f32_e32 v0, v0, v1
	v_cvt_pk_bf16_f32 v1, v3, s0
	v_mul_f32_e32 v17, v130, v17
	v_mul_f32_e32 v0, v129, v0
	ds_write_b16 v2, v1
	v_cvt_pk_bf16_f32 v1, v16, s0
	ds_write_b16 v2, v1 offset:64
	v_cvt_pk_bf16_f32 v1, v17, s0
	v_cvt_pk_bf16_f32 v0, v0, s0
	ds_write_b16 v2, v1 offset:128
	ds_write_b16 v2, v0 offset:192
	ds_read_b128 v[0:3], v134 offset:32
	ds_read_b128 v[16:19], v134 offset:160
	s_waitcnt lgkmcnt(0)
	v_mul_f32_e32 v20, v20, v16
	v_mul_f32_e32 v4, v4, v16
	v_fma_f32 v20, v84, v0, -v20
	v_fma_f32 v4, v68, v0, -v4
	v_mul_f32_e32 v33, v20, v20
	v_mul_f32_e32 v34, v36, v16
	v_fmac_f32_e32 v33, v4, v4
	v_fma_f32 v34, v100, v0, -v34
	v_mul_f32_e32 v16, v52, v16
	v_fmac_f32_e32 v33, v34, v34
	v_fma_f32 v0, v116, v0, -v16
	v_fmac_f32_e32 v33, v0, v0
	ds_swizzle_b32 v16, v33 offset:swizzle(SWAP,1)
	s_waitcnt lgkmcnt(0)
	v_add_f32_e32 v16, v33, v16
	ds_swizzle_b32 v33, v16 offset:swizzle(SWAP,2)
	s_waitcnt lgkmcnt(0)
	v_add_f32_e32 v16, v16, v33
	ds_swizzle_b32 v33, v16 offset:swizzle(SWAP,4)
	s_waitcnt lgkmcnt(0)
	v_add_f32_e32 v16, v16, v33
	ds_swizzle_b32 v33, v16 offset:swizzle(SWAP,8)
	s_waitcnt lgkmcnt(0)
	v_add_f32_e32 v16, v16, v33
	ds_swizzle_b32 v33, v16 offset:swizzle(SWAP,16)
	s_waitcnt lgkmcnt(0)
	v_add_f32_e32 v16, v16, v33
	v_fmamk_f32 v16, v16, 0x3c000000, v204
	v_rsq_f32_e32 v16, v16
	s_nop 0
	v_mul_f32_e32 v16, v133, v16
	v_mul_f32_e32 v4, v4, v16
	v_mul_f32_e32 v4, v132, v4
	v_mul_f32_e32 v20, v20, v16
	v_mul_f32_e32 v20, v131, v20
	v_mul_f32_e32 v33, v34, v16
	v_cvt_pk_bf16_f32 v4, v4, s0
	v_mul_f32_e32 v33, v130, v33
	v_mul_f32_e32 v0, v0, v16
	ds_write_b16 v32, v4 offset:2048
	v_cvt_pk_bf16_f32 v4, v20, s0
	v_mul_f32_e32 v0, v129, v0
	ds_write_b16 v32, v4 offset:2112
	v_cvt_pk_bf16_f32 v4, v33, s0
	ds_write_b16 v32, v4 offset:2176
	v_cvt_pk_bf16_f32 v0, v0, s0
	v_mul_f32_e32 v4, v21, v17
	ds_write_b16 v32, v0 offset:2240
	v_mul_f32_e32 v0, v5, v17
	v_fma_f32 v4, v85, v1, -v4
	v_fma_f32 v0, v69, v1, -v0
	v_mul_f32_e32 v5, v4, v4
	v_mul_f32_e32 v16, v37, v17
	v_fmac_f32_e32 v5, v0, v0
	v_fma_f32 v16, v101, v1, -v16
	v_mul_f32_e32 v17, v53, v17
	v_fmac_f32_e32 v5, v16, v16
	v_fma_f32 v1, v117, v1, -v17
	v_fmac_f32_e32 v5, v1, v1
	ds_swizzle_b32 v17, v5 offset:swizzle(SWAP,1)
	s_waitcnt lgkmcnt(0)
	v_add_f32_e32 v5, v5, v17
	ds_swizzle_b32 v17, v5 offset:swizzle(SWAP,2)
	s_waitcnt lgkmcnt(0)
	v_add_f32_e32 v5, v5, v17
	ds_swizzle_b32 v17, v5 offset:swizzle(SWAP,4)
	s_waitcnt lgkmcnt(0)
	v_add_f32_e32 v5, v5, v17
	ds_swizzle_b32 v17, v5 offset:swizzle(SWAP,8)
	s_waitcnt lgkmcnt(0)
	v_add_f32_e32 v5, v5, v17
	ds_swizzle_b32 v17, v5 offset:swizzle(SWAP,16)
	s_waitcnt lgkmcnt(0)
	v_add_f32_e32 v5, v5, v17
	v_fmamk_f32 v5, v5, 0x3c000000, v204
	v_rsq_f32_e32 v5, v5
	s_nop 0
	v_mul_f32_e32 v5, v133, v5
	v_mul_f32_e32 v0, v0, v5
	v_mul_f32_e32 v0, v132, v0
	v_mul_f32_e32 v4, v4, v5
	v_mul_f32_e32 v4, v131, v4
	v_mul_f32_e32 v16, v16, v5
	v_cvt_pk_bf16_f32 v0, v0, s0
	v_mul_f32_e32 v16, v130, v16
	v_mul_f32_e32 v1, v1, v5
	ds_write_b16 v32, v0 offset:2304
	v_cvt_pk_bf16_f32 v0, v4, s0
	v_mul_f32_e32 v1, v129, v1
	ds_write_b16 v32, v0 offset:2368
	v_cvt_pk_bf16_f32 v0, v16, s0
	ds_write_b16 v32, v0 offset:2432
	v_cvt_pk_bf16_f32 v0, v1, s0
	v_mul_f32_e32 v1, v22, v18
	ds_write_b16 v32, v0 offset:2496
	v_mul_f32_e32 v0, v6, v18
	v_fma_f32 v1, v86, v2, -v1
	v_fma_f32 v0, v70, v2, -v0
	v_mul_f32_e32 v4, v1, v1
	v_mul_f32_e32 v5, v38, v18
	v_fmac_f32_e32 v4, v0, v0
	v_fma_f32 v5, v102, v2, -v5
	v_mul_f32_e32 v6, v54, v18
	v_fmac_f32_e32 v4, v5, v5
	v_fma_f32 v2, v118, v2, -v6
	v_fmac_f32_e32 v4, v2, v2
	ds_swizzle_b32 v6, v4 offset:swizzle(SWAP,1)
	s_waitcnt lgkmcnt(0)
	v_add_f32_e32 v4, v4, v6
	ds_swizzle_b32 v6, v4 offset:swizzle(SWAP,2)
	s_waitcnt lgkmcnt(0)
	v_add_f32_e32 v4, v4, v6
	ds_swizzle_b32 v6, v4 offset:swizzle(SWAP,4)
	s_waitcnt lgkmcnt(0)
	v_add_f32_e32 v4, v4, v6
	ds_swizzle_b32 v6, v4 offset:swizzle(SWAP,8)
	s_waitcnt lgkmcnt(0)
	v_add_f32_e32 v4, v4, v6
	ds_swizzle_b32 v6, v4 offset:swizzle(SWAP,16)
	s_waitcnt lgkmcnt(0)
	v_add_f32_e32 v4, v4, v6
	v_fmamk_f32 v4, v4, 0x3c000000, v204
	v_rsq_f32_e32 v4, v4
	s_nop 0
	v_mul_f32_e32 v4, v133, v4
	v_mul_f32_e32 v0, v0, v4
	v_mul_f32_e32 v0, v132, v0
	v_mul_f32_e32 v1, v1, v4
	v_mul_f32_e32 v1, v131, v1
	v_mul_f32_e32 v5, v5, v4
	v_cvt_pk_bf16_f32 v0, v0, s0
	v_mul_f32_e32 v5, v130, v5
	v_mul_f32_e32 v2, v2, v4
	ds_write_b16 v32, v0 offset:2560
	v_cvt_pk_bf16_f32 v0, v1, s0
	v_mul_f32_e32 v2, v129, v2
	ds_write_b16 v32, v0 offset:2624
	v_cvt_pk_bf16_f32 v0, v5, s0
	ds_write_b16 v32, v0 offset:2688
	v_cvt_pk_bf16_f32 v0, v2, s0
	v_mul_f32_e32 v1, v23, v19
	ds_write_b16 v32, v0 offset:2752
	v_mul_f32_e32 v0, v7, v19
	v_fma_f32 v1, v87, v3, -v1
	v_fma_f32 v0, v71, v3, -v0
	v_mul_f32_e32 v2, v1, v1
	v_mul_f32_e32 v4, v39, v19
	v_fmac_f32_e32 v2, v0, v0
	v_fma_f32 v4, v103, v3, -v4
	v_mul_f32_e32 v5, v55, v19
	v_fmac_f32_e32 v2, v4, v4
	v_fma_f32 v3, v119, v3, -v5
	v_fmac_f32_e32 v2, v3, v3
	ds_swizzle_b32 v5, v2 offset:swizzle(SWAP,1)
	s_waitcnt lgkmcnt(0)
	v_add_f32_e32 v2, v2, v5
	ds_swizzle_b32 v5, v2 offset:swizzle(SWAP,2)
	s_waitcnt lgkmcnt(0)
	v_add_f32_e32 v2, v2, v5
	ds_swizzle_b32 v5, v2 offset:swizzle(SWAP,4)
	s_waitcnt lgkmcnt(0)
	v_add_f32_e32 v2, v2, v5
	ds_swizzle_b32 v5, v2 offset:swizzle(SWAP,8)
	s_waitcnt lgkmcnt(0)
	v_add_f32_e32 v2, v2, v5
	ds_swizzle_b32 v5, v2 offset:swizzle(SWAP,16)
	s_waitcnt lgkmcnt(0)
	v_add_f32_e32 v2, v2, v5
	v_fmamk_f32 v2, v2, 0x3c000000, v204
	v_rsq_f32_e32 v2, v2
	s_nop 0
	v_mul_f32_e32 v2, v133, v2
	v_mul_f32_e32 v0, v0, v2
	v_mul_f32_e32 v0, v132, v0
	v_mul_f32_e32 v1, v1, v2
	v_mul_f32_e32 v1, v131, v1
	v_mul_f32_e32 v4, v4, v2
	v_cvt_pk_bf16_f32 v0, v0, s0
	v_mul_f32_e32 v4, v130, v4
	v_mul_f32_e32 v2, v3, v2
	ds_write_b16 v32, v0 offset:2816
	v_cvt_pk_bf16_f32 v0, v1, s0
	v_mul_f32_e32 v2, v129, v2
	ds_write_b16 v32, v0 offset:2880
	v_cvt_pk_bf16_f32 v0, v4, s0
	ds_write_b16 v32, v0 offset:2944
	v_cvt_pk_bf16_f32 v0, v2, s0
	ds_write_b16 v32, v0 offset:3008
	ds_read_b128 v[0:3], v134 offset:64
	ds_read_b128 v[4:7], v134 offset:192
	s_waitcnt lgkmcnt(0)
	v_mul_f32_e32 v16, v24, v4
	v_mul_f32_e32 v8, v8, v4
	v_fma_f32 v16, v88, v0, -v16
	v_fma_f32 v8, v72, v0, -v8
	v_mul_f32_e32 v17, v16, v16
	v_mul_f32_e32 v18, v40, v4
	v_fmac_f32_e32 v17, v8, v8
	v_fma_f32 v18, v104, v0, -v18
	v_mul_f32_e32 v4, v56, v4
	v_fmac_f32_e32 v17, v18, v18
	v_fma_f32 v0, v120, v0, -v4
	v_fmac_f32_e32 v17, v0, v0
	ds_swizzle_b32 v4, v17 offset:swizzle(SWAP,1)
	s_waitcnt lgkmcnt(0)
	v_add_f32_e32 v4, v17, v4
	ds_swizzle_b32 v17, v4 offset:swizzle(SWAP,2)
	s_waitcnt lgkmcnt(0)
	v_add_f32_e32 v4, v4, v17
	ds_swizzle_b32 v17, v4 offset:swizzle(SWAP,4)
	s_waitcnt lgkmcnt(0)
	v_add_f32_e32 v4, v4, v17
	ds_swizzle_b32 v17, v4 offset:swizzle(SWAP,8)
	s_waitcnt lgkmcnt(0)
	v_add_f32_e32 v4, v4, v17
	ds_swizzle_b32 v17, v4 offset:swizzle(SWAP,16)
	s_waitcnt lgkmcnt(0)
	v_add_f32_e32 v4, v4, v17
	v_fmamk_f32 v4, v4, 0x3c000000, v204
	v_rsq_f32_e32 v4, v4
	s_nop 0
	v_mul_f32_e32 v4, v133, v4
	v_mul_f32_e32 v8, v8, v4
	v_mul_f32_e32 v8, v132, v8
	v_mul_f32_e32 v16, v16, v4
	v_mul_f32_e32 v16, v131, v16
	v_mul_f32_e32 v17, v18, v4
	v_mul_f32_e32 v0, v0, v4
	v_cvt_pk_bf16_f32 v4, v8, s0
	v_mul_f32_e32 v17, v130, v17
	ds_write_b16 v32, v4 offset:4096
	v_cvt_pk_bf16_f32 v4, v16, s0
	v_mul_f32_e32 v0, v129, v0
	ds_write_b16 v32, v4 offset:4160
	v_cvt_pk_bf16_f32 v4, v17, s0
	ds_write_b16 v32, v4 offset:4224
	v_cvt_pk_bf16_f32 v0, v0, s0
	v_mul_f32_e32 v4, v25, v5
	ds_write_b16 v32, v0 offset:4288
	v_mul_f32_e32 v0, v9, v5
	v_fma_f32 v4, v89, v1, -v4
	v_fma_f32 v0, v73, v1, -v0
	v_mul_f32_e32 v8, v4, v4
	v_mul_f32_e32 v9, v41, v5
	v_fmac_f32_e32 v8, v0, v0
	v_fma_f32 v9, v105, v1, -v9
	v_mul_f32_e32 v5, v57, v5
	v_fmac_f32_e32 v8, v9, v9
	v_fma_f32 v1, v121, v1, -v5
	v_fmac_f32_e32 v8, v1, v1
	ds_swizzle_b32 v5, v8 offset:swizzle(SWAP,1)
	s_waitcnt lgkmcnt(0)
	v_add_f32_e32 v5, v8, v5
	ds_swizzle_b32 v8, v5 offset:swizzle(SWAP,2)
	s_waitcnt lgkmcnt(0)
	v_add_f32_e32 v5, v5, v8
	ds_swizzle_b32 v8, v5 offset:swizzle(SWAP,4)
	s_waitcnt lgkmcnt(0)
	v_add_f32_e32 v5, v5, v8
	ds_swizzle_b32 v8, v5 offset:swizzle(SWAP,8)
	s_waitcnt lgkmcnt(0)
	v_add_f32_e32 v5, v5, v8
	ds_swizzle_b32 v8, v5 offset:swizzle(SWAP,16)
	s_waitcnt lgkmcnt(0)
	v_add_f32_e32 v5, v5, v8
	v_fmamk_f32 v5, v5, 0x3c000000, v204
	v_rsq_f32_e32 v5, v5
	s_nop 0
	v_mul_f32_e32 v5, v133, v5
	v_mul_f32_e32 v0, v0, v5
	v_mul_f32_e32 v0, v132, v0
	v_mul_f32_e32 v4, v4, v5
	v_mul_f32_e32 v4, v131, v4
	v_mul_f32_e32 v8, v9, v5
	v_cvt_pk_bf16_f32 v0, v0, s0
	v_mul_f32_e32 v8, v130, v8
	v_mul_f32_e32 v1, v1, v5
	ds_write_b16 v32, v0 offset:4352
	v_cvt_pk_bf16_f32 v0, v4, s0
	v_mul_f32_e32 v1, v129, v1
	ds_write_b16 v32, v0 offset:4416
	v_cvt_pk_bf16_f32 v0, v8, s0
	ds_write_b16 v32, v0 offset:4480
	v_cvt_pk_bf16_f32 v0, v1, s0
	v_mul_f32_e32 v1, v26, v6
	ds_write_b16 v32, v0 offset:4544
	v_mul_f32_e32 v0, v10, v6
	v_fma_f32 v1, v90, v2, -v1
	v_fma_f32 v0, v74, v2, -v0
	v_mul_f32_e32 v4, v1, v1
	v_mul_f32_e32 v5, v42, v6
	v_fmac_f32_e32 v4, v0, v0
	v_fma_f32 v5, v106, v2, -v5
	v_mul_f32_e32 v6, v58, v6
	v_fmac_f32_e32 v4, v5, v5
	v_fma_f32 v2, v122, v2, -v6
	v_fmac_f32_e32 v4, v2, v2
	ds_swizzle_b32 v6, v4 offset:swizzle(SWAP,1)
	s_waitcnt lgkmcnt(0)
	v_add_f32_e32 v4, v4, v6
	ds_swizzle_b32 v6, v4 offset:swizzle(SWAP,2)
	s_waitcnt lgkmcnt(0)
	v_add_f32_e32 v4, v4, v6
	ds_swizzle_b32 v6, v4 offset:swizzle(SWAP,4)
	s_waitcnt lgkmcnt(0)
	v_add_f32_e32 v4, v4, v6
	ds_swizzle_b32 v6, v4 offset:swizzle(SWAP,8)
	s_waitcnt lgkmcnt(0)
	v_add_f32_e32 v4, v4, v6
	ds_swizzle_b32 v6, v4 offset:swizzle(SWAP,16)
	s_waitcnt lgkmcnt(0)
	v_add_f32_e32 v4, v4, v6
	v_fmamk_f32 v4, v4, 0x3c000000, v204
	v_rsq_f32_e32 v4, v4
	s_nop 0
	v_mul_f32_e32 v4, v133, v4
	v_mul_f32_e32 v0, v0, v4
	v_mul_f32_e32 v0, v132, v0
	v_mul_f32_e32 v1, v1, v4
	v_mul_f32_e32 v1, v131, v1
	v_mul_f32_e32 v5, v5, v4
	v_cvt_pk_bf16_f32 v0, v0, s0
	v_mul_f32_e32 v5, v130, v5
	v_mul_f32_e32 v2, v2, v4
	ds_write_b16 v32, v0 offset:4608
	v_cvt_pk_bf16_f32 v0, v1, s0
	v_mul_f32_e32 v2, v129, v2
	ds_write_b16 v32, v0 offset:4672
	v_cvt_pk_bf16_f32 v0, v5, s0
	ds_write_b16 v32, v0 offset:4736
	v_cvt_pk_bf16_f32 v0, v2, s0
	v_mul_f32_e32 v1, v27, v7
	ds_write_b16 v32, v0 offset:4800
	v_mul_f32_e32 v0, v11, v7
	v_fma_f32 v1, v91, v3, -v1
	v_fma_f32 v0, v75, v3, -v0
	v_mul_f32_e32 v2, v1, v1
	v_mul_f32_e32 v4, v43, v7
	v_fmac_f32_e32 v2, v0, v0
	v_fma_f32 v4, v107, v3, -v4
	v_mul_f32_e32 v5, v59, v7
	v_fmac_f32_e32 v2, v4, v4
	v_fma_f32 v3, v123, v3, -v5
	v_fmac_f32_e32 v2, v3, v3
	ds_swizzle_b32 v5, v2 offset:swizzle(SWAP,1)
	s_waitcnt lgkmcnt(0)
	v_add_f32_e32 v2, v2, v5
	ds_swizzle_b32 v5, v2 offset:swizzle(SWAP,2)
	s_waitcnt lgkmcnt(0)
	v_add_f32_e32 v2, v2, v5
	ds_swizzle_b32 v5, v2 offset:swizzle(SWAP,4)
	s_waitcnt lgkmcnt(0)
	v_add_f32_e32 v2, v2, v5
	ds_swizzle_b32 v5, v2 offset:swizzle(SWAP,8)
	s_waitcnt lgkmcnt(0)
	v_add_f32_e32 v2, v2, v5
	ds_swizzle_b32 v5, v2 offset:swizzle(SWAP,16)
	s_waitcnt lgkmcnt(0)
	v_add_f32_e32 v2, v2, v5
	v_fmamk_f32 v2, v2, 0x3c000000, v204
	v_rsq_f32_e32 v2, v2
	s_nop 0
	v_mul_f32_e32 v2, v133, v2
	v_mul_f32_e32 v0, v0, v2
	v_mul_f32_e32 v0, v132, v0
	v_mul_f32_e32 v1, v1, v2
	v_mul_f32_e32 v1, v131, v1
	v_mul_f32_e32 v4, v4, v2
	v_cvt_pk_bf16_f32 v0, v0, s0
	v_mul_f32_e32 v4, v130, v4
	v_mul_f32_e32 v2, v3, v2
	ds_write_b16 v32, v0 offset:4864
	v_cvt_pk_bf16_f32 v0, v1, s0
	v_mul_f32_e32 v2, v129, v2
	ds_write_b16 v32, v0 offset:4928
	v_cvt_pk_bf16_f32 v0, v4, s0
	ds_write_b16 v32, v0 offset:4992
	v_cvt_pk_bf16_f32 v0, v2, s0
	ds_write_b16 v32, v0 offset:5056
	ds_read_b128 v[0:3], v134 offset:96
	ds_read_b128 v[4:7], v134 offset:224
	s_waitcnt lgkmcnt(0)
	v_mul_f32_e32 v9, v28, v4
	v_mul_f32_e32 v8, v12, v4
	v_fma_f32 v9, v92, v0, -v9
	v_fma_f32 v8, v76, v0, -v8
	v_mul_f32_e32 v10, v9, v9
	v_mul_f32_e32 v11, v44, v4
	v_fmac_f32_e32 v10, v8, v8
	v_fma_f32 v11, v108, v0, -v11
	v_mul_f32_e32 v4, v60, v4
	v_fmac_f32_e32 v10, v11, v11
	v_fma_f32 v0, v124, v0, -v4
	v_fmac_f32_e32 v10, v0, v0
	ds_swizzle_b32 v4, v10 offset:swizzle(SWAP,1)
	s_waitcnt lgkmcnt(0)
	v_add_f32_e32 v4, v10, v4
	ds_swizzle_b32 v10, v4 offset:swizzle(SWAP,2)
	s_waitcnt lgkmcnt(0)
	v_add_f32_e32 v4, v4, v10
	ds_swizzle_b32 v10, v4 offset:swizzle(SWAP,4)
	s_waitcnt lgkmcnt(0)
	v_add_f32_e32 v4, v4, v10
	ds_swizzle_b32 v10, v4 offset:swizzle(SWAP,8)
	s_waitcnt lgkmcnt(0)
	v_add_f32_e32 v4, v4, v10
	ds_swizzle_b32 v10, v4 offset:swizzle(SWAP,16)
	s_waitcnt lgkmcnt(0)
	v_add_f32_e32 v4, v4, v10
	v_fmamk_f32 v4, v4, 0x3c000000, v204
	v_rsq_f32_e32 v4, v4
	s_nop 0
	v_mul_f32_e32 v4, v133, v4
	v_mul_f32_e32 v8, v8, v4
	v_mul_f32_e32 v8, v132, v8
	v_mul_f32_e32 v9, v9, v4
	v_mul_f32_e32 v9, v131, v9
	v_mul_f32_e32 v10, v11, v4
	v_mul_f32_e32 v0, v0, v4
	v_cvt_pk_bf16_f32 v4, v8, s0
	v_mul_f32_e32 v10, v130, v10
	ds_write_b16 v32, v4 offset:6144
	v_cvt_pk_bf16_f32 v4, v9, s0
	v_mul_f32_e32 v0, v129, v0
	ds_write_b16 v32, v4 offset:6208
	v_cvt_pk_bf16_f32 v4, v10, s0
	ds_write_b16 v32, v4 offset:6272
	v_cvt_pk_bf16_f32 v0, v0, s0
	v_mul_f32_e32 v4, v29, v5
	ds_write_b16 v32, v0 offset:6336
	v_mul_f32_e32 v0, v13, v5
	v_fma_f32 v4, v93, v1, -v4
	v_fma_f32 v0, v77, v1, -v0
	v_mul_f32_e32 v8, v4, v4
	v_mul_f32_e32 v9, v45, v5
	v_fmac_f32_e32 v8, v0, v0
	v_fma_f32 v9, v109, v1, -v9
	v_mul_f32_e32 v5, v61, v5
	v_fmac_f32_e32 v8, v9, v9
	v_fma_f32 v1, v125, v1, -v5
	v_fmac_f32_e32 v8, v1, v1
	ds_swizzle_b32 v5, v8 offset:swizzle(SWAP,1)
	s_waitcnt lgkmcnt(0)
	v_add_f32_e32 v5, v8, v5
	ds_swizzle_b32 v8, v5 offset:swizzle(SWAP,2)
	s_waitcnt lgkmcnt(0)
	v_add_f32_e32 v5, v5, v8
	ds_swizzle_b32 v8, v5 offset:swizzle(SWAP,4)
	s_waitcnt lgkmcnt(0)
	v_add_f32_e32 v5, v5, v8
	ds_swizzle_b32 v8, v5 offset:swizzle(SWAP,8)
	s_waitcnt lgkmcnt(0)
	v_add_f32_e32 v5, v5, v8
	ds_swizzle_b32 v8, v5 offset:swizzle(SWAP,16)
	s_waitcnt lgkmcnt(0)
	v_add_f32_e32 v5, v5, v8
	v_fmamk_f32 v5, v5, 0x3c000000, v204
	v_rsq_f32_e32 v5, v5
	s_nop 0
	v_mul_f32_e32 v5, v133, v5
	v_mul_f32_e32 v0, v0, v5
	v_mul_f32_e32 v0, v132, v0
	v_mul_f32_e32 v4, v4, v5
	v_mul_f32_e32 v4, v131, v4
	v_mul_f32_e32 v8, v9, v5
	v_cvt_pk_bf16_f32 v0, v0, s0
	v_mul_f32_e32 v8, v130, v8
	v_mul_f32_e32 v1, v1, v5
	ds_write_b16 v32, v0 offset:6400
	v_cvt_pk_bf16_f32 v0, v4, s0
	v_mul_f32_e32 v1, v129, v1
	ds_write_b16 v32, v0 offset:6464
	v_cvt_pk_bf16_f32 v0, v8, s0
	ds_write_b16 v32, v0 offset:6528
	v_cvt_pk_bf16_f32 v0, v1, s0
	v_mul_f32_e32 v1, v30, v6
	ds_write_b16 v32, v0 offset:6592
	v_mul_f32_e32 v0, v14, v6
	v_fma_f32 v1, v94, v2, -v1
	v_fma_f32 v0, v78, v2, -v0
	v_mul_f32_e32 v4, v1, v1
	v_mul_f32_e32 v5, v46, v6
	v_fmac_f32_e32 v4, v0, v0
	v_fma_f32 v5, v110, v2, -v5
	v_mul_f32_e32 v6, v62, v6
	v_fmac_f32_e32 v4, v5, v5
	v_fma_f32 v2, v126, v2, -v6
	v_fmac_f32_e32 v4, v2, v2
	ds_swizzle_b32 v6, v4 offset:swizzle(SWAP,1)
	s_waitcnt lgkmcnt(0)
	v_add_f32_e32 v4, v4, v6
	ds_swizzle_b32 v6, v4 offset:swizzle(SWAP,2)
	s_waitcnt lgkmcnt(0)
	v_add_f32_e32 v4, v4, v6
	ds_swizzle_b32 v6, v4 offset:swizzle(SWAP,4)
	s_waitcnt lgkmcnt(0)
	v_add_f32_e32 v4, v4, v6
	ds_swizzle_b32 v6, v4 offset:swizzle(SWAP,8)
	s_waitcnt lgkmcnt(0)
	v_add_f32_e32 v4, v4, v6
	ds_swizzle_b32 v6, v4 offset:swizzle(SWAP,16)
	s_waitcnt lgkmcnt(0)
	v_add_f32_e32 v4, v4, v6
	v_fmamk_f32 v4, v4, 0x3c000000, v204
	v_rsq_f32_e32 v4, v4
	s_nop 0
	v_mul_f32_e32 v4, v133, v4
	v_mul_f32_e32 v0, v0, v4
	v_mul_f32_e32 v0, v132, v0
	v_mul_f32_e32 v1, v1, v4
	v_mul_f32_e32 v1, v131, v1
	v_mul_f32_e32 v5, v5, v4
	v_cvt_pk_bf16_f32 v0, v0, s0
	v_mul_f32_e32 v5, v130, v5
	v_mul_f32_e32 v2, v2, v4
	ds_write_b16 v32, v0 offset:6656
	v_cvt_pk_bf16_f32 v0, v1, s0
	v_mul_f32_e32 v2, v129, v2
	ds_write_b16 v32, v0 offset:6720
	v_cvt_pk_bf16_f32 v0, v5, s0
	ds_write_b16 v32, v0 offset:6784
	v_cvt_pk_bf16_f32 v0, v2, s0
	v_mul_f32_e32 v1, v31, v7
	ds_write_b16 v32, v0 offset:6848
	v_mul_f32_e32 v0, v15, v7
	v_fma_f32 v1, v95, v3, -v1
	v_fma_f32 v0, v79, v3, -v0
	v_mul_f32_e32 v2, v1, v1
	v_mul_f32_e32 v4, v47, v7
	v_fmac_f32_e32 v2, v0, v0
	v_fma_f32 v4, v111, v3, -v4
	v_mul_f32_e32 v5, v63, v7
	v_fmac_f32_e32 v2, v4, v4
	v_fma_f32 v3, v127, v3, -v5
	v_fmac_f32_e32 v2, v3, v3
	ds_swizzle_b32 v5, v2 offset:swizzle(SWAP,1)
	s_waitcnt lgkmcnt(0)
	v_add_f32_e32 v2, v2, v5
	ds_swizzle_b32 v5, v2 offset:swizzle(SWAP,2)
	s_waitcnt lgkmcnt(0)
	v_add_f32_e32 v2, v2, v5
	ds_swizzle_b32 v5, v2 offset:swizzle(SWAP,4)
	s_waitcnt lgkmcnt(0)
	v_add_f32_e32 v2, v2, v5
	ds_swizzle_b32 v5, v2 offset:swizzle(SWAP,8)
	s_waitcnt lgkmcnt(0)
	v_add_f32_e32 v2, v2, v5
	ds_swizzle_b32 v5, v2 offset:swizzle(SWAP,16)
	s_waitcnt lgkmcnt(0)
	v_add_f32_e32 v2, v2, v5
	v_fmamk_f32 v2, v2, 0x3c000000, v204
	v_rsq_f32_e32 v2, v2
	s_nop 0
	v_mul_f32_e32 v2, v133, v2
	v_mul_f32_e32 v0, v0, v2
	v_mul_f32_e32 v0, v132, v0
	v_mul_f32_e32 v1, v1, v2
	v_mul_f32_e32 v1, v131, v1
	v_mul_f32_e32 v4, v4, v2
	v_cvt_pk_bf16_f32 v0, v0, s0
	v_mul_f32_e32 v4, v130, v4
	v_mul_f32_e32 v2, v3, v2
	ds_write_b16 v32, v0 offset:6912
	v_cvt_pk_bf16_f32 v0, v1, s0
	v_mul_f32_e32 v2, v129, v2
	ds_write_b16 v32, v0 offset:6976
	v_cvt_pk_bf16_f32 v0, v4, s0
	ds_write_b16 v32, v0 offset:7040
	v_cvt_pk_bf16_f32 v0, v2, s0
	ds_write_b16 v32, v0 offset:7104
	v_lshlrev_b32_e32 v0, 4, v128
	v_and_b32_e32 v160, 0xf0, v0
	v_add_u32_e32 v6, s48, v160
	v_ashrrev_i32_e32 v4, 4, v128
	s_waitcnt lgkmcnt(0)
	v_lshl_add_u32 v0, v4, 8, v6
	ds_read_b128 v[0:3], v0
	v_ashrrev_i32_e32 v5, 31, v4
	v_lshl_add_u64 v[4:5], s[2:3], 0, v[4:5]
	v_lshlrev_b64 v[4:5], 11, v[4:5]
	v_lshl_add_u64 v[4:5], s[92:93], 0, v[4:5]
	v_lshl_add_u64 v[4:5], v[4:5], 0, v[160:161]
	s_waitcnt lgkmcnt(0)
	global_store_dwordx4 v[4:5], v[0:3], off nt
	s_nop 1
	v_add_u32_e32 v0, 64, v128
	v_ashrrev_i32_e32 v4, 4, v0
	v_lshl_add_u32 v0, v4, 8, v6
	ds_read_b128 v[0:3], v0
	v_ashrrev_i32_e32 v5, 31, v4
	v_lshl_add_u64 v[4:5], s[2:3], 0, v[4:5]
	v_lshlrev_b64 v[4:5], 11, v[4:5]
	v_lshl_add_u64 v[4:5], s[92:93], 0, v[4:5]
	v_lshl_add_u64 v[4:5], v[4:5], 0, v[160:161]
	s_waitcnt lgkmcnt(0)
	global_store_dwordx4 v[4:5], v[0:3], off nt
	s_nop 1
	v_add_u32_e32 v0, 0x80, v128
	v_ashrrev_i32_e32 v4, 4, v0
	v_lshl_add_u32 v0, v4, 8, v6
	ds_read_b128 v[0:3], v0
	v_ashrrev_i32_e32 v5, 31, v4
	v_lshl_add_u64 v[4:5], s[2:3], 0, v[4:5]
	v_lshlrev_b64 v[4:5], 11, v[4:5]
	v_lshl_add_u64 v[4:5], s[92:93], 0, v[4:5]
	v_lshl_add_u64 v[4:5], v[4:5], 0, v[160:161]
	s_waitcnt lgkmcnt(0)
	global_store_dwordx4 v[4:5], v[0:3], off nt
	s_nop 1
	v_add_u32_e32 v0, 0xc0, v128
	v_ashrrev_i32_e32 v4, 4, v0
	v_lshl_add_u32 v0, v4, 8, v6
	ds_read_b128 v[0:3], v0
	v_ashrrev_i32_e32 v5, 31, v4
	v_lshl_add_u64 v[4:5], s[2:3], 0, v[4:5]
	v_lshlrev_b64 v[4:5], 11, v[4:5]
	v_lshl_add_u64 v[4:5], s[92:93], 0, v[4:5]
	v_lshl_add_u64 v[4:5], v[4:5], 0, v[160:161]
	s_waitcnt lgkmcnt(0)
	global_store_dwordx4 v[4:5], v[0:3], off nt
	s_nop 1
	v_add_u32_e32 v0, 0x100, v128
	v_ashrrev_i32_e32 v4, 4, v0
	v_lshl_add_u32 v0, v4, 8, v6
	ds_read_b128 v[0:3], v0
	v_ashrrev_i32_e32 v5, 31, v4
	v_lshl_add_u64 v[4:5], s[2:3], 0, v[4:5]
	v_lshlrev_b64 v[4:5], 11, v[4:5]
	v_lshl_add_u64 v[4:5], s[92:93], 0, v[4:5]
	v_lshl_add_u64 v[4:5], v[4:5], 0, v[160:161]
	s_waitcnt lgkmcnt(0)
	global_store_dwordx4 v[4:5], v[0:3], off nt
	s_nop 1
	v_add_u32_e32 v0, 0x140, v128
	v_ashrrev_i32_e32 v4, 4, v0
	v_lshl_add_u32 v0, v4, 8, v6
	ds_read_b128 v[0:3], v0
	v_ashrrev_i32_e32 v5, 31, v4
	v_lshl_add_u64 v[4:5], s[2:3], 0, v[4:5]
	v_lshlrev_b64 v[4:5], 11, v[4:5]
	v_lshl_add_u64 v[4:5], s[92:93], 0, v[4:5]
	v_lshl_add_u64 v[4:5], v[4:5], 0, v[160:161]
	s_waitcnt lgkmcnt(0)
	global_store_dwordx4 v[4:5], v[0:3], off nt
	s_nop 1
	v_add_u32_e32 v0, 0x180, v128
	v_ashrrev_i32_e32 v4, 4, v0
	v_lshl_add_u32 v0, v4, 8, v6
	ds_read_b128 v[0:3], v0
	v_ashrrev_i32_e32 v5, 31, v4
	v_lshl_add_u64 v[4:5], s[2:3], 0, v[4:5]
	v_lshlrev_b64 v[4:5], 11, v[4:5]
	v_lshl_add_u64 v[4:5], s[92:93], 0, v[4:5]
	v_lshl_add_u64 v[4:5], v[4:5], 0, v[160:161]
	s_waitcnt lgkmcnt(0)
	global_store_dwordx4 v[4:5], v[0:3], off nt
	s_nop 1
	v_add_u32_e32 v0, 0x1c0, v128
	v_ashrrev_i32_e32 v4, 4, v0
	v_lshl_add_u32 v0, v4, 8, v6
	ds_read_b128 v[0:3], v0
	v_ashrrev_i32_e32 v5, 31, v4
	v_lshl_add_u64 v[4:5], s[2:3], 0, v[4:5]
	v_lshlrev_b64 v[4:5], 11, v[4:5]
	v_lshl_add_u64 v[4:5], s[92:93], 0, v[4:5]
	v_lshl_add_u64 v[4:5], v[4:5], 0, v[160:161]
	s_waitcnt lgkmcnt(0)
	global_store_dwordx4 v[4:5], v[0:3], off nt
	s_waitcnt vmcnt(0) lgkmcnt(0)
	s_barrier
	s_cbranch_scc1 .LBB0_419

.LBB0_540:
	v_lshl_add_u32 v140, s3, 8, v144
	v_lshl_or_b32 v138, s2, 8, v146
	v_ashrrev_i32_e32 v141, 31, v140
	v_ashrrev_i32_e32 v139, 31, v138
	v_lshlrev_b64 v[142:143], 10, v[140:141]
	v_lshl_add_u64 v[142:143], v[142:143], 0, v[138:139]
	v_lshlrev_b64 v[142:143], 1, v[142:143]
	v_lshl_add_u64 v[148:149], s[66:67], 0, v[142:143]
	global_load_dwordx4 v[148:151], v[148:149], off
	s_mov_b64 s[16:17], -1
	s_andn2_b64 vcc, exec, s[4:5]
	s_waitcnt vmcnt(0)
	v_lshlrev_b32_e32 v152, 16, v148
	v_and_b32_e32 v153, 0xffff0000, v148
	v_lshlrev_b32_e32 v154, 16, v149
	v_and_b32_e32 v155, 0xffff0000, v149
	v_lshl_add_u64 v[148:149], s[70:71], 0, v[142:143]
	v_lshlrev_b32_e32 v156, 16, v150
	v_and_b32_e32 v157, 0xffff0000, v150
	v_lshlrev_b32_e32 v158, 16, v151
	v_and_b32_e32 v159, 0xffff0000, v151
	global_load_dwordx4 v[148:151], v[148:149], off
	s_waitcnt vmcnt(0)
	v_lshlrev_b32_e32 v162, 16, v148
	v_and_b32_e32 v163, 0xffff0000, v148
	v_lshlrev_b32_e32 v148, 16, v149
	v_and_b32_e32 v149, 0xffff0000, v149
	v_lshlrev_b32_e32 v166, 16, v150
	v_and_b32_e32 v167, 0xffff0000, v150
	v_lshlrev_b32_e32 v150, 16, v151
	v_and_b32_e32 v151, 0xffff0000, v151
	v_pk_fma_f32 v[124:125], v[124:125], v[162:163], v[152:153]
	v_pk_fma_f32 v[126:127], v[126:127], v[148:149], v[154:155]
	v_pk_fma_f32 v[148:149], v[122:123], v[150:151], v[158:159]
	v_pk_fma_f32 v[122:123], v[120:121], v[166:167], v[156:157]
	v_cvt_pk_bf16_f32 v120, v124, v125
	v_cvt_pk_bf16_f32 v121, v126, v127
	v_lshl_add_u64 v[124:125], s[82:83], 0, v[142:143]
	v_or_b32_e32 v142, 0x100, v142
	v_cvt_pk_bf16_f32 v122, v122, v123
	v_cvt_pk_bf16_f32 v123, v148, v149
	global_store_dwordx4 v[124:125], v[120:123], off nt
	s_nop 1
	v_lshl_add_u64 v[120:121], s[66:67], 0, v[142:143]
	global_load_dwordx4 v[120:123], v[120:121], off
	s_waitcnt vmcnt(0)
	v_lshlrev_b32_e32 v124, 16, v120
	v_and_b32_e32 v125, 0xffff0000, v120
	v_lshlrev_b32_e32 v126, 16, v121
	v_and_b32_e32 v127, 0xffff0000, v121
	v_lshl_add_u64 v[120:121], s[70:71], 0, v[142:143]
	v_lshlrev_b32_e32 v148, 16, v122
	v_and_b32_e32 v149, 0xffff0000, v122
	v_lshlrev_b32_e32 v150, 16, v123
	v_and_b32_e32 v151, 0xffff0000, v123
	global_load_dwordx4 v[120:123], v[120:121], off
	s_waitcnt vmcnt(0)
	v_lshlrev_b32_e32 v152, 16, v120
	v_and_b32_e32 v153, 0xffff0000, v120
	v_lshlrev_b32_e32 v120, 16, v121
	v_and_b32_e32 v121, 0xffff0000, v121
	v_lshlrev_b32_e32 v154, 16, v122
	v_and_b32_e32 v155, 0xffff0000, v122
	v_lshlrev_b32_e32 v122, 16, v123
	v_and_b32_e32 v123, 0xffff0000, v123
	v_pk_fma_f32 v[116:117], v[116:117], v[152:153], v[124:125]
	v_pk_fma_f32 v[118:119], v[118:119], v[120:121], v[126:127]
	v_pk_fma_f32 v[120:121], v[114:115], v[122:123], v[150:151]
	v_pk_fma_f32 v[114:115], v[112:113], v[154:155], v[148:149]
	v_cvt_pk_bf16_f32 v112, v116, v117
	v_lshl_add_u64 v[116:117], s[82:83], 0, v[142:143]
	v_cvt_pk_bf16_f32 v113, v118, v119
	v_cvt_pk_bf16_f32 v114, v114, v115
	v_cvt_pk_bf16_f32 v115, v120, v121
	global_store_dwordx4 v[116:117], v[112:115], off nt
	s_nop 1
	v_or_b32_e32 v112, 16, v140
	v_ashrrev_i32_e32 v113, 31, v112
	v_lshlrev_b64 v[112:113], 10, v[112:113]
	v_lshl_add_u64 v[112:113], v[112:113], 0, v[138:139]
	v_lshlrev_b64 v[112:113], 1, v[112:113]
	v_lshl_add_u64 v[114:115], s[66:67], 0, v[112:113]
	global_load_dwordx4 v[114:117], v[114:115], off
	s_waitcnt vmcnt(0)
	v_lshlrev_b32_e32 v118, 16, v114
	v_and_b32_e32 v119, 0xffff0000, v114
	v_lshlrev_b32_e32 v120, 16, v115
	v_and_b32_e32 v121, 0xffff0000, v115
	v_lshl_add_u64 v[114:115], s[70:71], 0, v[112:113]
	v_lshlrev_b32_e32 v122, 16, v116
	v_and_b32_e32 v123, 0xffff0000, v116
	v_lshlrev_b32_e32 v124, 16, v117
	v_and_b32_e32 v125, 0xffff0000, v117
	global_load_dwordx4 v[114:117], v[114:115], off
	s_waitcnt vmcnt(0)
	v_lshlrev_b32_e32 v126, 16, v114
	v_and_b32_e32 v127, 0xffff0000, v114
	v_lshlrev_b32_e32 v114, 16, v115
	v_and_b32_e32 v115, 0xffff0000, v115
	v_lshlrev_b32_e32 v142, 16, v116
	v_and_b32_e32 v143, 0xffff0000, v116
	v_lshlrev_b32_e32 v116, 16, v117
	v_and_b32_e32 v117, 0xffff0000, v117
	v_pk_fma_f32 v[108:109], v[108:109], v[126:127], v[118:119]
	v_pk_fma_f32 v[110:111], v[110:111], v[114:115], v[120:121]
	v_pk_fma_f32 v[114:115], v[106:107], v[116:117], v[124:125]
	v_pk_fma_f32 v[106:107], v[104:105], v[142:143], v[122:123]
	v_cvt_pk_bf16_f32 v104, v108, v109
	v_cvt_pk_bf16_f32 v105, v110, v111
	v_lshl_add_u64 v[108:109], s[82:83], 0, v[112:113]
	v_or_b32_e32 v112, 0x100, v112
	v_cvt_pk_bf16_f32 v106, v106, v107
	v_cvt_pk_bf16_f32 v107, v114, v115
	global_store_dwordx4 v[108:109], v[104:107], off nt
	s_nop 1
	v_lshl_add_u64 v[104:105], s[66:67], 0, v[112:113]
	global_load_dwordx4 v[104:107], v[104:105], off
	s_waitcnt vmcnt(0)
	v_lshlrev_b32_e32 v108, 16, v104
	v_and_b32_e32 v109, 0xffff0000, v104
	v_lshlrev_b32_e32 v110, 16, v105
	v_and_b32_e32 v111, 0xffff0000, v105
	v_lshl_add_u64 v[104:105], s[70:71], 0, v[112:113]
	v_lshlrev_b32_e32 v114, 16, v106
	v_and_b32_e32 v115, 0xffff0000, v106
	v_lshlrev_b32_e32 v116, 16, v107
	v_and_b32_e32 v117, 0xffff0000, v107
	global_load_dwordx4 v[104:107], v[104:105], off
	s_waitcnt vmcnt(0)
	v_lshlrev_b32_e32 v118, 16, v104
	v_and_b32_e32 v119, 0xffff0000, v104
	v_lshlrev_b32_e32 v104, 16, v105
	v_and_b32_e32 v105, 0xffff0000, v105
	v_lshlrev_b32_e32 v120, 16, v106
	v_and_b32_e32 v121, 0xffff0000, v106
	v_lshlrev_b32_e32 v106, 16, v107
	v_and_b32_e32 v107, 0xffff0000, v107
	v_pk_fma_f32 v[100:101], v[100:101], v[118:119], v[108:109]
	v_pk_fma_f32 v[102:103], v[102:103], v[104:105], v[110:111]
	v_pk_fma_f32 v[104:105], v[98:99], v[106:107], v[116:117]
	v_pk_fma_f32 v[98:99], v[96:97], v[120:121], v[114:115]
	v_cvt_pk_bf16_f32 v96, v100, v101
	v_lshl_add_u64 v[100:101], s[82:83], 0, v[112:113]
	v_cvt_pk_bf16_f32 v97, v102, v103
	v_cvt_pk_bf16_f32 v98, v98, v99
	v_cvt_pk_bf16_f32 v99, v104, v105
	global_store_dwordx4 v[100:101], v[96:99], off nt
	s_nop 1
	v_or_b32_e32 v96, 32, v140
	v_ashrrev_i32_e32 v97, 31, v96
	v_lshlrev_b64 v[96:97], 10, v[96:97]
	v_lshl_add_u64 v[96:97], v[96:97], 0, v[138:139]
	v_lshlrev_b64 v[96:97], 1, v[96:97]
	v_lshl_add_u64 v[98:99], s[66:67], 0, v[96:97]
	global_load_dwordx4 v[98:101], v[98:99], off
	s_waitcnt vmcnt(0)
	v_lshlrev_b32_e32 v102, 16, v98
	v_and_b32_e32 v103, 0xffff0000, v98
	v_lshlrev_b32_e32 v104, 16, v99
	v_and_b32_e32 v105, 0xffff0000, v99
	v_lshl_add_u64 v[98:99], s[70:71], 0, v[96:97]
	v_lshlrev_b32_e32 v106, 16, v100
	v_and_b32_e32 v107, 0xffff0000, v100
	v_lshlrev_b32_e32 v108, 16, v101
	v_and_b32_e32 v109, 0xffff0000, v101
	global_load_dwordx4 v[98:101], v[98:99], off
	s_waitcnt vmcnt(0)
	v_lshlrev_b32_e32 v110, 16, v98
	v_and_b32_e32 v111, 0xffff0000, v98
	v_lshlrev_b32_e32 v98, 16, v99
	v_and_b32_e32 v99, 0xffff0000, v99
	v_lshlrev_b32_e32 v112, 16, v100
	v_and_b32_e32 v113, 0xffff0000, v100
	v_lshlrev_b32_e32 v100, 16, v101
	v_and_b32_e32 v101, 0xffff0000, v101
	v_pk_fma_f32 v[92:93], v[92:93], v[110:111], v[102:103]
	v_pk_fma_f32 v[94:95], v[94:95], v[98:99], v[104:105]
	v_pk_fma_f32 v[98:99], v[90:91], v[100:101], v[108:109]
	v_pk_fma_f32 v[90:91], v[88:89], v[112:113], v[106:107]
	v_cvt_pk_bf16_f32 v88, v92, v93
	v_cvt_pk_bf16_f32 v89, v94, v95
	v_lshl_add_u64 v[92:93], s[82:83], 0, v[96:97]
	v_or_b32_e32 v96, 0x100, v96
	v_cvt_pk_bf16_f32 v90, v90, v91
	v_cvt_pk_bf16_f32 v91, v98, v99
	global_store_dwordx4 v[92:93], v[88:91], off nt
	s_nop 1
	v_lshl_add_u64 v[88:89], s[66:67], 0, v[96:97]
	global_load_dwordx4 v[88:91], v[88:89], off
	s_waitcnt vmcnt(0)
	v_lshlrev_b32_e32 v92, 16, v88
	v_and_b32_e32 v93, 0xffff0000, v88
	v_lshlrev_b32_e32 v94, 16, v89
	v_and_b32_e32 v95, 0xffff0000, v89
	v_lshl_add_u64 v[88:89], s[70:71], 0, v[96:97]
	v_lshlrev_b32_e32 v98, 16, v90
	v_and_b32_e32 v99, 0xffff0000, v90
	v_lshlrev_b32_e32 v100, 16, v91
	v_and_b32_e32 v101, 0xffff0000, v91
	global_load_dwordx4 v[88:91], v[88:89], off
	s_waitcnt vmcnt(0)
	v_lshlrev_b32_e32 v102, 16, v88
	v_and_b32_e32 v103, 0xffff0000, v88
	v_lshlrev_b32_e32 v88, 16, v89
	v_and_b32_e32 v89, 0xffff0000, v89
	v_lshlrev_b32_e32 v104, 16, v90
	v_and_b32_e32 v105, 0xffff0000, v90
	v_lshlrev_b32_e32 v90, 16, v91
	v_and_b32_e32 v91, 0xffff0000, v91
	v_pk_fma_f32 v[84:85], v[84:85], v[102:103], v[92:93]
	v_pk_fma_f32 v[86:87], v[86:87], v[88:89], v[94:95]
	v_pk_fma_f32 v[88:89], v[82:83], v[90:91], v[100:101]
	v_pk_fma_f32 v[82:83], v[80:81], v[104:105], v[98:99]
	v_cvt_pk_bf16_f32 v80, v84, v85
	v_lshl_add_u64 v[84:85], s[82:83], 0, v[96:97]
	v_cvt_pk_bf16_f32 v81, v86, v87
	v_cvt_pk_bf16_f32 v82, v82, v83
	v_cvt_pk_bf16_f32 v83, v88, v89
	global_store_dwordx4 v[84:85], v[80:83], off nt
	s_nop 1
	v_or_b32_e32 v80, 48, v140
	v_ashrrev_i32_e32 v81, 31, v80
	v_lshlrev_b64 v[80:81], 10, v[80:81]
	v_lshl_add_u64 v[80:81], v[80:81], 0, v[138:139]
	v_lshlrev_b64 v[80:81], 1, v[80:81]
	v_lshl_add_u64 v[82:83], s[66:67], 0, v[80:81]
	global_load_dwordx4 v[82:85], v[82:83], off
	s_waitcnt vmcnt(0)
	v_lshlrev_b32_e32 v86, 16, v82
	v_and_b32_e32 v87, 0xffff0000, v82
	v_lshlrev_b32_e32 v88, 16, v83
	v_and_b32_e32 v89, 0xffff0000, v83
	v_lshl_add_u64 v[82:83], s[70:71], 0, v[80:81]
	v_lshlrev_b32_e32 v90, 16, v84
	v_and_b32_e32 v91, 0xffff0000, v84
	v_lshlrev_b32_e32 v92, 16, v85
	v_and_b32_e32 v93, 0xffff0000, v85
	global_load_dwordx4 v[82:85], v[82:83], off
	s_waitcnt vmcnt(0)
	v_lshlrev_b32_e32 v94, 16, v82
	v_and_b32_e32 v95, 0xffff0000, v82
	v_lshlrev_b32_e32 v82, 16, v83
	v_and_b32_e32 v83, 0xffff0000, v83
	v_lshlrev_b32_e32 v96, 16, v84
	v_and_b32_e32 v97, 0xffff0000, v84
	v_lshlrev_b32_e32 v84, 16, v85
	v_and_b32_e32 v85, 0xffff0000, v85
	v_pk_fma_f32 v[76:77], v[76:77], v[94:95], v[86:87]
	v_pk_fma_f32 v[78:79], v[78:79], v[82:83], v[88:89]
	v_pk_fma_f32 v[82:83], v[74:75], v[84:85], v[92:93]
	v_pk_fma_f32 v[74:75], v[72:73], v[96:97], v[90:91]
	v_cvt_pk_bf16_f32 v72, v76, v77
	v_cvt_pk_bf16_f32 v73, v78, v79
	v_lshl_add_u64 v[76:77], s[82:83], 0, v[80:81]
	v_or_b32_e32 v80, 0x100, v80
	v_cvt_pk_bf16_f32 v74, v74, v75
	v_cvt_pk_bf16_f32 v75, v82, v83
	global_store_dwordx4 v[76:77], v[72:75], off nt
	s_nop 1
	v_lshl_add_u64 v[72:73], s[66:67], 0, v[80:81]
	global_load_dwordx4 v[72:75], v[72:73], off
	s_waitcnt vmcnt(0)
	v_lshlrev_b32_e32 v76, 16, v72
	v_and_b32_e32 v77, 0xffff0000, v72
	v_lshlrev_b32_e32 v78, 16, v73
	v_and_b32_e32 v79, 0xffff0000, v73
	v_lshl_add_u64 v[72:73], s[70:71], 0, v[80:81]
	v_lshlrev_b32_e32 v82, 16, v74
	v_and_b32_e32 v83, 0xffff0000, v74
	v_lshlrev_b32_e32 v84, 16, v75
	v_and_b32_e32 v85, 0xffff0000, v75
	global_load_dwordx4 v[72:75], v[72:73], off
	s_waitcnt vmcnt(0)
	v_lshlrev_b32_e32 v86, 16, v72
	v_and_b32_e32 v87, 0xffff0000, v72
	v_lshlrev_b32_e32 v72, 16, v73
	v_and_b32_e32 v73, 0xffff0000, v73
	v_lshlrev_b32_e32 v88, 16, v74
	v_and_b32_e32 v89, 0xffff0000, v74
	v_lshlrev_b32_e32 v74, 16, v75
	v_and_b32_e32 v75, 0xffff0000, v75
	v_pk_fma_f32 v[68:69], v[68:69], v[86:87], v[76:77]
	v_pk_fma_f32 v[70:71], v[70:71], v[72:73], v[78:79]
	v_pk_fma_f32 v[72:73], v[66:67], v[74:75], v[84:85]
	v_pk_fma_f32 v[66:67], v[64:65], v[88:89], v[82:83]
	v_cvt_pk_bf16_f32 v64, v68, v69
	v_lshl_add_u64 v[68:69], s[82:83], 0, v[80:81]
	v_cvt_pk_bf16_f32 v65, v70, v71
	v_cvt_pk_bf16_f32 v66, v66, v67
	v_cvt_pk_bf16_f32 v67, v72, v73
	global_store_dwordx4 v[68:69], v[64:67], off nt
	s_nop 1
	v_add_u32_e32 v64, 0x80, v140
	v_ashrrev_i32_e32 v65, 31, v64
	v_lshlrev_b64 v[64:65], 10, v[64:65]
	v_lshl_add_u64 v[64:65], v[64:65], 0, v[138:139]
	v_lshlrev_b64 v[64:65], 1, v[64:65]
	v_lshl_add_u64 v[66:67], s[66:67], 0, v[64:65]
	global_load_dwordx4 v[66:69], v[66:67], off
	s_waitcnt vmcnt(0)
	v_lshlrev_b32_e32 v70, 16, v66
	v_and_b32_e32 v71, 0xffff0000, v66
	v_lshlrev_b32_e32 v72, 16, v67
	v_and_b32_e32 v73, 0xffff0000, v67
	v_lshl_add_u64 v[66:67], s[70:71], 0, v[64:65]
	v_lshlrev_b32_e32 v74, 16, v68
	v_and_b32_e32 v75, 0xffff0000, v68
	v_lshlrev_b32_e32 v76, 16, v69
	v_and_b32_e32 v77, 0xffff0000, v69
	global_load_dwordx4 v[66:69], v[66:67], off
	s_waitcnt vmcnt(0)
	v_lshlrev_b32_e32 v78, 16, v66
	v_and_b32_e32 v79, 0xffff0000, v66
	v_lshlrev_b32_e32 v66, 16, v67
	v_and_b32_e32 v67, 0xffff0000, v67
	v_lshlrev_b32_e32 v80, 16, v68
	v_and_b32_e32 v81, 0xffff0000, v68
	v_lshlrev_b32_e32 v68, 16, v69
	v_and_b32_e32 v69, 0xffff0000, v69
	v_pk_fma_f32 v[60:61], v[60:61], v[78:79], v[70:71]
	v_pk_fma_f32 v[62:63], v[62:63], v[66:67], v[72:73]
	v_pk_fma_f32 v[66:67], v[58:59], v[68:69], v[76:77]
	v_pk_fma_f32 v[58:59], v[56:57], v[80:81], v[74:75]
	v_cvt_pk_bf16_f32 v56, v60, v61
	v_cvt_pk_bf16_f32 v57, v62, v63
	v_lshl_add_u64 v[60:61], s[82:83], 0, v[64:65]
	v_or_b32_e32 v64, 0x100, v64
	v_cvt_pk_bf16_f32 v58, v58, v59
	v_cvt_pk_bf16_f32 v59, v66, v67
	global_store_dwordx4 v[60:61], v[56:59], off nt
	s_nop 1
	v_lshl_add_u64 v[56:57], s[66:67], 0, v[64:65]
	global_load_dwordx4 v[56:59], v[56:57], off
	s_waitcnt vmcnt(0)
	v_lshlrev_b32_e32 v60, 16, v56
	v_and_b32_e32 v61, 0xffff0000, v56
	v_lshlrev_b32_e32 v62, 16, v57
	v_and_b32_e32 v63, 0xffff0000, v57
	v_lshl_add_u64 v[56:57], s[70:71], 0, v[64:65]
	v_lshlrev_b32_e32 v66, 16, v58
	v_and_b32_e32 v67, 0xffff0000, v58
	v_lshlrev_b32_e32 v68, 16, v59
	v_and_b32_e32 v69, 0xffff0000, v59
	global_load_dwordx4 v[56:59], v[56:57], off
	s_waitcnt vmcnt(0)
	v_lshlrev_b32_e32 v70, 16, v56
	v_and_b32_e32 v71, 0xffff0000, v56
	v_lshlrev_b32_e32 v56, 16, v57
	v_and_b32_e32 v57, 0xffff0000, v57
	v_lshlrev_b32_e32 v72, 16, v58
	v_and_b32_e32 v73, 0xffff0000, v58
	v_lshlrev_b32_e32 v58, 16, v59
	v_and_b32_e32 v59, 0xffff0000, v59
	v_pk_fma_f32 v[52:53], v[52:53], v[70:71], v[60:61]
	v_pk_fma_f32 v[54:55], v[54:55], v[56:57], v[62:63]
	v_pk_fma_f32 v[56:57], v[50:51], v[58:59], v[68:69]
	v_pk_fma_f32 v[50:51], v[48:49], v[72:73], v[66:67]
	v_cvt_pk_bf16_f32 v48, v52, v53
	v_lshl_add_u64 v[52:53], s[82:83], 0, v[64:65]
	v_cvt_pk_bf16_f32 v49, v54, v55
	v_cvt_pk_bf16_f32 v50, v50, v51
	v_cvt_pk_bf16_f32 v51, v56, v57
	global_store_dwordx4 v[52:53], v[48:51], off nt
	s_nop 1
	v_add_u32_e32 v48, 0x90, v140
	v_ashrrev_i32_e32 v49, 31, v48
	v_lshlrev_b64 v[48:49], 10, v[48:49]
	v_lshl_add_u64 v[48:49], v[48:49], 0, v[138:139]
	v_lshlrev_b64 v[48:49], 1, v[48:49]
	v_lshl_add_u64 v[50:51], s[66:67], 0, v[48:49]
	global_load_dwordx4 v[50:53], v[50:51], off
	s_waitcnt vmcnt(0)
	v_lshlrev_b32_e32 v54, 16, v50
	v_and_b32_e32 v55, 0xffff0000, v50
	v_lshlrev_b32_e32 v56, 16, v51
	v_and_b32_e32 v57, 0xffff0000, v51
	v_lshl_add_u64 v[50:51], s[70:71], 0, v[48:49]
	v_lshlrev_b32_e32 v58, 16, v52
	v_and_b32_e32 v59, 0xffff0000, v52
	v_lshlrev_b32_e32 v60, 16, v53
	v_and_b32_e32 v61, 0xffff0000, v53
	global_load_dwordx4 v[50:53], v[50:51], off
	s_waitcnt vmcnt(0)
	v_lshlrev_b32_e32 v62, 16, v50
	v_and_b32_e32 v63, 0xffff0000, v50
	v_lshlrev_b32_e32 v50, 16, v51
	v_and_b32_e32 v51, 0xffff0000, v51
	v_lshlrev_b32_e32 v64, 16, v52
	v_and_b32_e32 v65, 0xffff0000, v52
	v_lshlrev_b32_e32 v52, 16, v53
	v_and_b32_e32 v53, 0xffff0000, v53
	v_pk_fma_f32 v[44:45], v[44:45], v[62:63], v[54:55]
	v_pk_fma_f32 v[46:47], v[46:47], v[50:51], v[56:57]
	v_pk_fma_f32 v[50:51], v[42:43], v[52:53], v[60:61]
	v_pk_fma_f32 v[42:43], v[40:41], v[64:65], v[58:59]
	v_cvt_pk_bf16_f32 v40, v44, v45
	v_cvt_pk_bf16_f32 v41, v46, v47
	v_lshl_add_u64 v[44:45], s[82:83], 0, v[48:49]
	v_or_b32_e32 v48, 0x100, v48
	v_cvt_pk_bf16_f32 v42, v42, v43
	v_cvt_pk_bf16_f32 v43, v50, v51
	global_store_dwordx4 v[44:45], v[40:43], off nt
	s_nop 1
	v_lshl_add_u64 v[40:41], s[66:67], 0, v[48:49]
	global_load_dwordx4 v[40:43], v[40:41], off
	s_waitcnt vmcnt(0)
	v_lshlrev_b32_e32 v44, 16, v40
	v_and_b32_e32 v45, 0xffff0000, v40
	v_lshlrev_b32_e32 v46, 16, v41
	v_and_b32_e32 v47, 0xffff0000, v41
	v_lshl_add_u64 v[40:41], s[70:71], 0, v[48:49]
	v_lshlrev_b32_e32 v50, 16, v42
	v_and_b32_e32 v51, 0xffff0000, v42
	v_lshlrev_b32_e32 v52, 16, v43
	v_and_b32_e32 v53, 0xffff0000, v43
	global_load_dwordx4 v[40:43], v[40:41], off
	s_waitcnt vmcnt(0)
	v_lshlrev_b32_e32 v54, 16, v40
	v_and_b32_e32 v55, 0xffff0000, v40
	v_lshlrev_b32_e32 v40, 16, v41
	v_and_b32_e32 v41, 0xffff0000, v41
	v_lshlrev_b32_e32 v56, 16, v42
	v_and_b32_e32 v57, 0xffff0000, v42
	v_lshlrev_b32_e32 v42, 16, v43
	v_and_b32_e32 v43, 0xffff0000, v43
	v_pk_fma_f32 v[36:37], v[36:37], v[54:55], v[44:45]
	v_pk_fma_f32 v[38:39], v[38:39], v[40:41], v[46:47]
	v_pk_fma_f32 v[40:41], v[34:35], v[42:43], v[52:53]
	v_pk_fma_f32 v[34:35], v[32:33], v[56:57], v[50:51]
	v_cvt_pk_bf16_f32 v32, v36, v37
	v_lshl_add_u64 v[36:37], s[82:83], 0, v[48:49]
	v_cvt_pk_bf16_f32 v33, v38, v39
	v_cvt_pk_bf16_f32 v34, v34, v35
	v_cvt_pk_bf16_f32 v35, v40, v41
	global_store_dwordx4 v[36:37], v[32:35], off nt
	s_nop 1
	v_add_u32_e32 v32, 0xa0, v140
	v_ashrrev_i32_e32 v33, 31, v32
	v_lshlrev_b64 v[32:33], 10, v[32:33]
	v_lshl_add_u64 v[32:33], v[32:33], 0, v[138:139]
	v_lshlrev_b64 v[32:33], 1, v[32:33]
	v_lshl_add_u64 v[34:35], s[66:67], 0, v[32:33]
	global_load_dwordx4 v[34:37], v[34:35], off
	s_waitcnt vmcnt(0)
	v_lshlrev_b32_e32 v38, 16, v34
	v_and_b32_e32 v39, 0xffff0000, v34
	v_lshlrev_b32_e32 v40, 16, v35
	v_and_b32_e32 v41, 0xffff0000, v35
	v_lshl_add_u64 v[34:35], s[70:71], 0, v[32:33]
	v_lshlrev_b32_e32 v42, 16, v36
	v_and_b32_e32 v43, 0xffff0000, v36
	v_lshlrev_b32_e32 v44, 16, v37
	v_and_b32_e32 v45, 0xffff0000, v37
	global_load_dwordx4 v[34:37], v[34:35], off
	s_waitcnt vmcnt(0)
	v_lshlrev_b32_e32 v46, 16, v34
	v_and_b32_e32 v47, 0xffff0000, v34
	v_lshlrev_b32_e32 v34, 16, v35
	v_and_b32_e32 v35, 0xffff0000, v35
	v_lshlrev_b32_e32 v48, 16, v36
	v_and_b32_e32 v49, 0xffff0000, v36
	v_lshlrev_b32_e32 v36, 16, v37
	v_and_b32_e32 v37, 0xffff0000, v37
	v_pk_fma_f32 v[28:29], v[28:29], v[46:47], v[38:39]
	v_pk_fma_f32 v[30:31], v[30:31], v[34:35], v[40:41]
	v_pk_fma_f32 v[34:35], v[26:27], v[36:37], v[44:45]
	v_pk_fma_f32 v[26:27], v[24:25], v[48:49], v[42:43]
	v_cvt_pk_bf16_f32 v24, v28, v29
	v_cvt_pk_bf16_f32 v25, v30, v31
	v_lshl_add_u64 v[28:29], s[82:83], 0, v[32:33]
	v_or_b32_e32 v32, 0x100, v32
	v_cvt_pk_bf16_f32 v26, v26, v27
	v_cvt_pk_bf16_f32 v27, v34, v35
	global_store_dwordx4 v[28:29], v[24:27], off nt
	s_nop 1
	v_lshl_add_u64 v[24:25], s[66:67], 0, v[32:33]
	global_load_dwordx4 v[24:27], v[24:25], off
	s_waitcnt vmcnt(0)
	v_lshlrev_b32_e32 v28, 16, v24
	v_and_b32_e32 v29, 0xffff0000, v24
	v_lshlrev_b32_e32 v30, 16, v25
	v_and_b32_e32 v31, 0xffff0000, v25
	v_lshl_add_u64 v[24:25], s[70:71], 0, v[32:33]
	v_lshlrev_b32_e32 v34, 16, v26
	v_and_b32_e32 v35, 0xffff0000, v26
	v_lshlrev_b32_e32 v36, 16, v27
	v_and_b32_e32 v37, 0xffff0000, v27
	global_load_dwordx4 v[24:27], v[24:25], off
	s_waitcnt vmcnt(0)
	v_lshlrev_b32_e32 v38, 16, v24
	v_and_b32_e32 v39, 0xffff0000, v24
	v_lshlrev_b32_e32 v24, 16, v25
	v_and_b32_e32 v25, 0xffff0000, v25
	v_lshlrev_b32_e32 v40, 16, v26
	v_and_b32_e32 v41, 0xffff0000, v26
	v_lshlrev_b32_e32 v26, 16, v27
	v_and_b32_e32 v27, 0xffff0000, v27
	v_pk_fma_f32 v[20:21], v[20:21], v[38:39], v[28:29]
	v_pk_fma_f32 v[22:23], v[22:23], v[24:25], v[30:31]
	v_pk_fma_f32 v[24:25], v[18:19], v[26:27], v[36:37]
	v_pk_fma_f32 v[18:19], v[16:17], v[40:41], v[34:35]
	v_cvt_pk_bf16_f32 v16, v20, v21
	v_lshl_add_u64 v[20:21], s[82:83], 0, v[32:33]
	v_cvt_pk_bf16_f32 v17, v22, v23
	v_cvt_pk_bf16_f32 v18, v18, v19
	v_cvt_pk_bf16_f32 v19, v24, v25
	global_store_dwordx4 v[20:21], v[16:19], off nt
	s_nop 1
	v_add_u32_e32 v16, 0xb0, v140
	v_ashrrev_i32_e32 v17, 31, v16
	v_lshlrev_b64 v[16:17], 10, v[16:17]
	v_lshl_add_u64 v[16:17], v[16:17], 0, v[138:139]
	v_lshlrev_b64 v[16:17], 1, v[16:17]
	v_lshl_add_u64 v[18:19], s[66:67], 0, v[16:17]
	global_load_dwordx4 v[18:21], v[18:19], off
	s_waitcnt vmcnt(0)
	v_lshlrev_b32_e32 v22, 16, v18
	v_and_b32_e32 v23, 0xffff0000, v18
	v_lshlrev_b32_e32 v24, 16, v19
	v_and_b32_e32 v25, 0xffff0000, v19
	v_lshl_add_u64 v[18:19], s[70:71], 0, v[16:17]
	v_lshlrev_b32_e32 v26, 16, v20
	v_and_b32_e32 v27, 0xffff0000, v20
	v_lshlrev_b32_e32 v28, 16, v21
	v_and_b32_e32 v29, 0xffff0000, v21
	global_load_dwordx4 v[18:21], v[18:19], off
	s_waitcnt vmcnt(0)
	v_lshlrev_b32_e32 v30, 16, v18
	v_and_b32_e32 v31, 0xffff0000, v18
	v_lshlrev_b32_e32 v18, 16, v19
	v_and_b32_e32 v19, 0xffff0000, v19
	v_lshlrev_b32_e32 v32, 16, v20
	v_and_b32_e32 v33, 0xffff0000, v20
	v_lshlrev_b32_e32 v20, 16, v21
	v_and_b32_e32 v21, 0xffff0000, v21
	v_pk_fma_f32 v[12:13], v[12:13], v[30:31], v[22:23]
	v_pk_fma_f32 v[14:15], v[14:15], v[18:19], v[24:25]
	v_pk_fma_f32 v[18:19], v[10:11], v[20:21], v[28:29]
	v_pk_fma_f32 v[10:11], v[8:9], v[32:33], v[26:27]
	v_cvt_pk_bf16_f32 v8, v12, v13
	v_cvt_pk_bf16_f32 v9, v14, v15
	v_lshl_add_u64 v[12:13], s[82:83], 0, v[16:17]
	v_or_b32_e32 v16, 0x100, v16
	v_cvt_pk_bf16_f32 v10, v10, v11
	v_cvt_pk_bf16_f32 v11, v18, v19
	global_store_dwordx4 v[12:13], v[8:11], off nt
	s_nop 1
	v_lshl_add_u64 v[8:9], s[66:67], 0, v[16:17]
	global_load_dwordx4 v[8:11], v[8:9], off
	s_waitcnt vmcnt(0)
	v_lshlrev_b32_e32 v12, 16, v8
	v_and_b32_e32 v13, 0xffff0000, v8
	v_lshlrev_b32_e32 v14, 16, v9
	v_and_b32_e32 v15, 0xffff0000, v9
	v_lshl_add_u64 v[8:9], s[70:71], 0, v[16:17]
	v_lshlrev_b32_e32 v18, 16, v10
	v_and_b32_e32 v19, 0xffff0000, v10
	v_lshlrev_b32_e32 v20, 16, v11
	v_and_b32_e32 v21, 0xffff0000, v11
	global_load_dwordx4 v[8:11], v[8:9], off
	s_waitcnt vmcnt(0)
	v_lshlrev_b32_e32 v22, 16, v8
	v_and_b32_e32 v23, 0xffff0000, v8
	v_lshlrev_b32_e32 v8, 16, v9
	v_and_b32_e32 v9, 0xffff0000, v9
	v_lshlrev_b32_e32 v24, 16, v10
	v_and_b32_e32 v25, 0xffff0000, v10
	v_lshlrev_b32_e32 v10, 16, v11
	v_and_b32_e32 v11, 0xffff0000, v11
	v_pk_fma_f32 v[4:5], v[4:5], v[22:23], v[12:13]
	v_pk_fma_f32 v[6:7], v[6:7], v[8:9], v[14:15]
	v_pk_fma_f32 v[8:9], v[2:3], v[10:11], v[20:21]
	v_pk_fma_f32 v[2:3], v[0:1], v[24:25], v[18:19]
	v_cvt_pk_bf16_f32 v0, v4, v5
	v_lshl_add_u64 v[4:5], s[82:83], 0, v[16:17]
	v_cvt_pk_bf16_f32 v1, v6, v7
	v_cvt_pk_bf16_f32 v2, v2, v3
	v_cvt_pk_bf16_f32 v3, v8, v9
	global_store_dwordx4 v[4:5], v[0:3], off nt
	s_cbranch_vccnz .LBB0_529
	s_andn2_b64 vcc, exec, s[0:1]
	s_cbranch_vccnz .LBB0_528
	s_barrier
	s_branch .LBB0_528

.LBB0_614:
	v_lshl_add_u32 v178, s56, 8, v186
	v_ashrrev_i32_e32 v179, 31, v178
	v_lshlrev_b64 v[162:163], 10, v[178:179]
	v_lshl_add_u64 v[180:181], v[162:163], 0, v[176:177]
	v_lshlrev_b64 v[162:163], 2, v[180:181]
	v_lshl_add_u64 v[182:183], s[10:11], 0, v[162:163]
	global_load_dwordx4 v[190:193], v[182:183], off
	global_load_dwordx4 v[194:197], v[182:183], off offset:16
	s_and_b64 vcc, exec, s[8:9]
	v_lshl_add_u64 v[184:185], s[72:73], 0, v[162:163]
	s_waitcnt vmcnt(0)
	v_pk_fma_f32 v[142:143], v[142:143], v[78:79], v[192:193]
	v_pk_fma_f32 v[140:141], v[140:141], v[76:77], v[190:191]
	v_pk_fma_f32 v[138:139], v[138:139], v[86:87], v[196:197]
	v_pk_fma_f32 v[136:137], v[136:137], v[84:85], v[194:195]
	v_mov_b32_e32 v190, 0
	global_store_dwordx4 v[184:185], v[140:143], off nt
	global_store_dwordx4 v[184:185], v[136:139], off offset:16 nt
	s_cbranch_vccnz .LBB0_616
	v_pk_mul_f32 v[162:163], v[142:143], v[142:143]
	v_pk_mul_f32 v[190:191], v[140:141], v[140:141]
	v_pk_mul_f32 v[140:141], v[168:169], v[140:141]
	v_pk_mov_b32 v[192:193], v[190:191], v[162:163] op_sel:[1,0]
	v_mov_b32_e32 v191, v163
	v_pk_add_f32 v[162:163], v[192:193], v[190:191]
	v_pk_mul_f32 v[190:191], v[138:139], v[138:139]
	v_pk_mul_f32 v[192:193], v[136:137], v[136:137]
	v_mov_b32_e32 v194, v190
	v_mov_b32_e32 v195, v192
	v_mov_b32_e32 v192, v191
	v_pk_add_f32 v[190:191], v[194:195], v[192:193]
	v_add_f32_e32 v162, v162, v163
	v_add_f32_e32 v162, v162, v191
	v_add_f32_e32 v190, v190, v162
	v_pk_mul_f32 v[162:163], v[174:175], v[138:139]
	v_pk_mul_f32 v[138:139], v[154:155], v[136:137]
	v_cvt_pk_bf16_f32 v136, v140, v141
	v_lshl_add_u64 v[140:141], v[180:181], 1, s[44:45]
	v_pk_mul_f32 v[142:143], v[170:171], v[142:143]
	s_nop 0
	v_cvt_pk_bf16_f32 v137, v142, v143
	v_cvt_pk_bf16_f32 v138, v138, v139
	v_cvt_pk_bf16_f32 v139, v162, v163
	global_store_dwordx4 v[140:141], v[136:139], off nt
.LBB0_616:
	global_load_dwordx4 v[136:139], v[182:183], off offset:512
	s_nop 0
	global_load_dwordx4 v[140:143], v[182:183], off offset:528
	s_and_b64 vcc, exec, s[8:9]
	s_waitcnt vmcnt(1)
	v_pk_fma_f32 v[134:135], v[134:135], v[70:71], v[138:139]
	v_pk_fma_f32 v[132:133], v[132:133], v[68:69], v[136:137]
	s_waitcnt vmcnt(0)
	v_pk_fma_f32 v[130:131], v[130:131], v[82:83], v[142:143]
	v_pk_fma_f32 v[128:129], v[128:129], v[80:81], v[140:141]
	global_store_dwordx4 v[184:185], v[132:135], off offset:512 nt
	global_store_dwordx4 v[184:185], v[128:131], off offset:528 nt
	s_cbranch_vccnz .LBB0_620
	v_pk_mul_f32 v[142:143], v[172:173], v[130:131]
	v_mul_f32_e32 v131, v131, v131
	v_fmac_f32_e32 v131, v130, v130
	v_mul_f32_e32 v130, v133, v133
	v_pk_mul_f32 v[136:137], v[158:159], v[132:133]
	v_fmac_f32_e32 v130, v132, v132
	v_mul_f32_e32 v132, v135, v135
	v_pk_mul_f32 v[162:163], v[156:157], v[128:129]
	v_fmac_f32_e32 v132, v134, v134
	v_mul_f32_e32 v129, v129, v129
	v_add_f32_e32 v130, v130, v132
	v_fmac_f32_e32 v129, v128, v128
	v_add_f32_e32 v128, v130, v129
	v_add_f32_e32 v128, v131, v128
	v_add_f32_e32 v130, v190, v128
	ds_swizzle_b32 v131, v130 offset:swizzle(SWAP,16)
	v_lshlrev_b64 v[140:141], 1, v[180:181]
	v_or_b32_e32 v140, 0x100, v140
	v_pk_mul_f32 v[138:139], v[166:167], v[134:135]
	v_lshl_add_u64 v[128:129], s[44:45], 0, v[140:141]
	v_cvt_pk_bf16_f32 v136, v136, v137
	v_cvt_pk_bf16_f32 v137, v138, v139
	v_cvt_pk_bf16_f32 v138, v162, v163
	v_cvt_pk_bf16_f32 v139, v142, v143
	global_store_dwordx4 v[128:129], v[136:139], off nt
	s_waitcnt lgkmcnt(0)
	v_add_f32_e32 v128, v130, v131
	v_mov_b32_e32 v129, v128
	s_nop 1
	v_permlane32_swap_b32_e32 v128, v129
	s_and_saveexec_b64 s[26:27], s[4:5]
	s_cbranch_execz .LBB0_619
	v_lshl_add_u64 v[130:131], v[178:179], 2, s[50:51]
	v_add_f32_e32 v128, v128, v129
	global_atomic_add_f32 v[130:131], v128, off

.LBB0_620:
	s_nop 0
	v_or_b32_e32 v128, 16, v178
	v_ashrrev_i32_e32 v129, 31, v128
	v_lshlrev_b64 v[130:131], 10, v[128:129]
	v_lshl_add_u64 v[130:131], v[130:131], 0, v[176:177]
	v_lshlrev_b64 v[134:135], 2, v[130:131]
	v_lshl_add_u64 v[132:133], s[10:11], 0, v[134:135]
	global_load_dwordx4 v[136:139], v[132:133], off
	global_load_dwordx4 v[140:143], v[132:133], off offset:16
	s_and_b64 vcc, exec, s[8:9]
	v_lshl_add_u64 v[134:135], s[72:73], 0, v[134:135]
	s_waitcnt vmcnt(1)
	v_pk_fma_f32 v[126:127], v[126:127], v[78:79], v[138:139]
	v_pk_fma_f32 v[124:125], v[124:125], v[76:77], v[136:137]
	s_waitcnt vmcnt(0)
	v_pk_fma_f32 v[122:123], v[122:123], v[86:87], v[142:143]
	v_pk_fma_f32 v[120:121], v[120:121], v[84:85], v[140:141]
	v_mov_b32_e32 v136, 0
	global_store_dwordx4 v[134:135], v[124:127], off nt
	global_store_dwordx4 v[134:135], v[120:123], off offset:16 nt
	s_cbranch_vccnz .LBB0_622
	v_pk_mul_f32 v[136:137], v[126:127], v[126:127]
	v_pk_mul_f32 v[138:139], v[124:125], v[124:125]
	v_pk_mul_f32 v[124:125], v[168:169], v[124:125]
	v_pk_mov_b32 v[140:141], v[138:139], v[136:137] op_sel:[1,0]
	v_mov_b32_e32 v139, v137
	v_pk_add_f32 v[136:137], v[140:141], v[138:139]
	v_pk_mul_f32 v[138:139], v[122:123], v[122:123]
	v_pk_mul_f32 v[140:141], v[120:121], v[120:121]
	v_mov_b32_e32 v142, v138
	v_mov_b32_e32 v143, v140
	v_mov_b32_e32 v140, v139
	v_pk_add_f32 v[138:139], v[142:143], v[140:141]
	v_add_f32_e32 v136, v136, v137
	v_add_f32_e32 v136, v136, v139
	v_add_f32_e32 v136, v138, v136
	v_pk_mul_f32 v[138:139], v[174:175], v[122:123]
	v_pk_mul_f32 v[122:123], v[154:155], v[120:121]
	v_cvt_pk_bf16_f32 v120, v124, v125
	v_lshl_add_u64 v[124:125], v[130:131], 1, s[44:45]
	v_pk_mul_f32 v[126:127], v[170:171], v[126:127]
	s_nop 0
	v_cvt_pk_bf16_f32 v121, v126, v127
	v_cvt_pk_bf16_f32 v122, v122, v123
	v_cvt_pk_bf16_f32 v123, v138, v139
	global_store_dwordx4 v[124:125], v[120:123], off nt
.LBB0_622:
	global_load_dwordx4 v[120:123], v[132:133], off offset:512
	s_nop 0
	global_load_dwordx4 v[124:127], v[132:133], off offset:528
	s_and_b64 vcc, exec, s[8:9]
	s_waitcnt vmcnt(1)
	v_pk_fma_f32 v[118:119], v[118:119], v[70:71], v[122:123]
	v_pk_fma_f32 v[116:117], v[116:117], v[68:69], v[120:121]
	s_waitcnt vmcnt(0)
	v_pk_fma_f32 v[114:115], v[114:115], v[82:83], v[126:127]
	v_pk_fma_f32 v[112:113], v[112:113], v[80:81], v[124:125]
	global_store_dwordx4 v[134:135], v[116:119], off offset:512 nt
	global_store_dwordx4 v[134:135], v[112:115], off offset:528 nt
	s_cbranch_vccnz .LBB0_626
	v_pk_mul_f32 v[126:127], v[172:173], v[114:115]
	v_mul_f32_e32 v115, v115, v115
	v_fmac_f32_e32 v115, v114, v114
	v_mul_f32_e32 v114, v117, v117
	v_pk_mul_f32 v[120:121], v[158:159], v[116:117]
	v_fmac_f32_e32 v114, v116, v116
	v_mul_f32_e32 v116, v119, v119
	v_lshlrev_b64 v[124:125], 1, v[130:131]
	v_pk_mul_f32 v[130:131], v[156:157], v[112:113]
	v_fmac_f32_e32 v116, v118, v118
	v_mul_f32_e32 v113, v113, v113
	v_add_f32_e32 v114, v114, v116
	v_fmac_f32_e32 v113, v112, v112
	v_add_f32_e32 v112, v114, v113
	v_add_f32_e32 v112, v115, v112
	v_add_f32_e32 v114, v136, v112
	ds_swizzle_b32 v115, v114 offset:swizzle(SWAP,16)
	v_or_b32_e32 v124, 0x100, v124
	v_pk_mul_f32 v[122:123], v[166:167], v[118:119]
	v_lshl_add_u64 v[112:113], s[44:45], 0, v[124:125]
	v_cvt_pk_bf16_f32 v120, v120, v121
	v_cvt_pk_bf16_f32 v121, v122, v123
	v_cvt_pk_bf16_f32 v122, v130, v131
	v_cvt_pk_bf16_f32 v123, v126, v127
	global_store_dwordx4 v[112:113], v[120:123], off nt
	s_waitcnt lgkmcnt(0)
	v_add_f32_e32 v112, v114, v115
	v_mov_b32_e32 v113, v112
	s_nop 1
	v_permlane32_swap_b32_e32 v112, v113
	s_and_saveexec_b64 s[26:27], s[4:5]
	s_cbranch_execz .LBB0_625
	v_lshl_add_u64 v[114:115], v[128:129], 2, s[50:51]
	v_add_f32_e32 v112, v112, v113
	global_atomic_add_f32 v[114:115], v112, off

.LBB0_626:
	s_nop 0
	v_or_b32_e32 v112, 32, v178
	v_ashrrev_i32_e32 v113, 31, v112
	v_lshlrev_b64 v[114:115], 10, v[112:113]
	v_lshl_add_u64 v[114:115], v[114:115], 0, v[176:177]
	v_lshlrev_b64 v[118:119], 2, v[114:115]
	v_lshl_add_u64 v[116:117], s[10:11], 0, v[118:119]
	global_load_dwordx4 v[120:123], v[116:117], off
	global_load_dwordx4 v[124:127], v[116:117], off offset:16
	s_and_b64 vcc, exec, s[8:9]
	v_lshl_add_u64 v[118:119], s[72:73], 0, v[118:119]
	s_waitcnt vmcnt(1)
	v_pk_fma_f32 v[110:111], v[110:111], v[78:79], v[122:123]
	v_pk_fma_f32 v[108:109], v[108:109], v[76:77], v[120:121]
	s_waitcnt vmcnt(0)
	v_pk_fma_f32 v[106:107], v[106:107], v[86:87], v[126:127]
	v_pk_fma_f32 v[104:105], v[104:105], v[84:85], v[124:125]
	v_mov_b32_e32 v120, 0
	global_store_dwordx4 v[118:119], v[108:111], off nt
	global_store_dwordx4 v[118:119], v[104:107], off offset:16 nt
	s_cbranch_vccnz .LBB0_628
	v_pk_mul_f32 v[120:121], v[110:111], v[110:111]
	v_pk_mul_f32 v[122:123], v[108:109], v[108:109]
	v_pk_mul_f32 v[108:109], v[168:169], v[108:109]
	v_pk_mov_b32 v[124:125], v[122:123], v[120:121] op_sel:[1,0]
	v_mov_b32_e32 v123, v121
	v_pk_add_f32 v[120:121], v[124:125], v[122:123]
	v_pk_mul_f32 v[122:123], v[106:107], v[106:107]
	v_pk_mul_f32 v[124:125], v[104:105], v[104:105]
	v_mov_b32_e32 v126, v122
	v_mov_b32_e32 v127, v124
	v_mov_b32_e32 v124, v123
	v_pk_add_f32 v[122:123], v[126:127], v[124:125]
	v_add_f32_e32 v120, v120, v121
	v_add_f32_e32 v120, v120, v123
	v_add_f32_e32 v120, v122, v120
	v_pk_mul_f32 v[122:123], v[174:175], v[106:107]
	v_pk_mul_f32 v[106:107], v[154:155], v[104:105]
	v_cvt_pk_bf16_f32 v104, v108, v109
	v_lshl_add_u64 v[108:109], v[114:115], 1, s[44:45]
	v_pk_mul_f32 v[110:111], v[170:171], v[110:111]
	s_nop 0
	v_cvt_pk_bf16_f32 v105, v110, v111
	v_cvt_pk_bf16_f32 v106, v106, v107
	v_cvt_pk_bf16_f32 v107, v122, v123
	global_store_dwordx4 v[108:109], v[104:107], off nt
.LBB0_628:
	global_load_dwordx4 v[104:107], v[116:117], off offset:512
	s_nop 0
	global_load_dwordx4 v[108:111], v[116:117], off offset:528
	s_and_b64 vcc, exec, s[8:9]
	s_waitcnt vmcnt(1)
	v_pk_fma_f32 v[102:103], v[102:103], v[70:71], v[106:107]
	v_pk_fma_f32 v[100:101], v[100:101], v[68:69], v[104:105]
	s_waitcnt vmcnt(0)
	v_pk_fma_f32 v[98:99], v[98:99], v[82:83], v[110:111]
	v_pk_fma_f32 v[96:97], v[96:97], v[80:81], v[108:109]
	global_store_dwordx4 v[118:119], v[100:103], off offset:512 nt
	global_store_dwordx4 v[118:119], v[96:99], off offset:528 nt
	s_cbranch_vccnz .LBB0_632
	v_pk_mul_f32 v[110:111], v[172:173], v[98:99]
	v_mul_f32_e32 v99, v99, v99
	v_fmac_f32_e32 v99, v98, v98
	v_mul_f32_e32 v98, v101, v101
	v_pk_mul_f32 v[104:105], v[158:159], v[100:101]
	v_fmac_f32_e32 v98, v100, v100
	v_mul_f32_e32 v100, v103, v103
	v_lshlrev_b64 v[108:109], 1, v[114:115]
	v_pk_mul_f32 v[114:115], v[156:157], v[96:97]
	v_fmac_f32_e32 v100, v102, v102
	v_mul_f32_e32 v97, v97, v97
	v_add_f32_e32 v98, v98, v100
	v_fmac_f32_e32 v97, v96, v96
	v_add_f32_e32 v96, v98, v97
	v_add_f32_e32 v96, v99, v96
	v_add_f32_e32 v98, v120, v96
	ds_swizzle_b32 v99, v98 offset:swizzle(SWAP,16)
	v_or_b32_e32 v108, 0x100, v108
	v_pk_mul_f32 v[106:107], v[166:167], v[102:103]
	v_lshl_add_u64 v[96:97], s[44:45], 0, v[108:109]
	v_cvt_pk_bf16_f32 v104, v104, v105
	v_cvt_pk_bf16_f32 v105, v106, v107
	v_cvt_pk_bf16_f32 v106, v114, v115
	v_cvt_pk_bf16_f32 v107, v110, v111
	global_store_dwordx4 v[96:97], v[104:107], off nt
	s_waitcnt lgkmcnt(0)
	v_add_f32_e32 v96, v98, v99
	v_mov_b32_e32 v97, v96
	s_nop 1
	v_permlane32_swap_b32_e32 v96, v97
	s_and_saveexec_b64 s[26:27], s[4:5]
	s_cbranch_execz .LBB0_631
	v_lshl_add_u64 v[98:99], v[112:113], 2, s[50:51]
	v_add_f32_e32 v96, v96, v97
	global_atomic_add_f32 v[98:99], v96, off

.LBB0_632:
	s_nop 0
	v_or_b32_e32 v96, 48, v178
	v_ashrrev_i32_e32 v97, 31, v96
	v_lshlrev_b64 v[98:99], 10, v[96:97]
	v_lshl_add_u64 v[98:99], v[98:99], 0, v[176:177]
	v_lshlrev_b64 v[102:103], 2, v[98:99]
	v_lshl_add_u64 v[100:101], s[10:11], 0, v[102:103]
	global_load_dwordx4 v[104:107], v[100:101], off
	global_load_dwordx4 v[108:111], v[100:101], off offset:16
	s_and_b64 vcc, exec, s[8:9]
	v_lshl_add_u64 v[102:103], s[72:73], 0, v[102:103]
	s_waitcnt vmcnt(1)
	v_pk_fma_f32 v[94:95], v[94:95], v[78:79], v[106:107]
	v_pk_fma_f32 v[92:93], v[92:93], v[76:77], v[104:105]
	s_waitcnt vmcnt(0)
	v_pk_fma_f32 v[90:91], v[90:91], v[86:87], v[110:111]
	v_pk_fma_f32 v[88:89], v[88:89], v[84:85], v[108:109]
	v_mov_b32_e32 v104, 0
	global_store_dwordx4 v[102:103], v[92:95], off nt
	global_store_dwordx4 v[102:103], v[88:91], off offset:16 nt
	s_cbranch_vccnz .LBB0_634
	v_pk_mul_f32 v[104:105], v[94:95], v[94:95]
	v_pk_mul_f32 v[106:107], v[92:93], v[92:93]
	v_pk_mul_f32 v[92:93], v[168:169], v[92:93]
	v_pk_mov_b32 v[108:109], v[106:107], v[104:105] op_sel:[1,0]
	v_mov_b32_e32 v107, v105
	v_pk_add_f32 v[104:105], v[108:109], v[106:107]
	v_pk_mul_f32 v[106:107], v[90:91], v[90:91]
	v_pk_mul_f32 v[108:109], v[88:89], v[88:89]
	v_mov_b32_e32 v110, v106
	v_mov_b32_e32 v111, v108
	v_mov_b32_e32 v108, v107
	v_pk_add_f32 v[106:107], v[110:111], v[108:109]
	v_add_f32_e32 v104, v104, v105
	v_add_f32_e32 v104, v104, v107
	v_add_f32_e32 v104, v106, v104
	v_pk_mul_f32 v[106:107], v[174:175], v[90:91]
	v_pk_mul_f32 v[90:91], v[154:155], v[88:89]
	v_cvt_pk_bf16_f32 v88, v92, v93
	v_lshl_add_u64 v[92:93], v[98:99], 1, s[44:45]
	v_pk_mul_f32 v[94:95], v[170:171], v[94:95]
	s_nop 0
	v_cvt_pk_bf16_f32 v89, v94, v95
	v_cvt_pk_bf16_f32 v90, v90, v91
	v_cvt_pk_bf16_f32 v91, v106, v107
	global_store_dwordx4 v[92:93], v[88:91], off nt
.LBB0_634:
	global_load_dwordx4 v[88:91], v[100:101], off offset:512
	s_nop 0
	global_load_dwordx4 v[92:95], v[100:101], off offset:528
	s_and_b64 vcc, exec, s[8:9]
	s_waitcnt vmcnt(1)
	v_pk_fma_f32 v[74:75], v[74:75], v[70:71], v[90:91]
	v_pk_fma_f32 v[72:73], v[72:73], v[68:69], v[88:89]
	s_waitcnt vmcnt(0)
	v_pk_fma_f32 v[66:67], v[66:67], v[82:83], v[94:95]
	v_pk_fma_f32 v[64:65], v[64:65], v[80:81], v[92:93]
	global_store_dwordx4 v[102:103], v[72:75], off offset:512 nt
	global_store_dwordx4 v[102:103], v[64:67], off offset:528 nt
	s_cbranch_vccnz .LBB0_638
	v_pk_mul_f32 v[94:95], v[172:173], v[66:67]
	v_mul_f32_e32 v67, v67, v67
	v_fmac_f32_e32 v67, v66, v66
	v_mul_f32_e32 v66, v73, v73
	v_pk_mul_f32 v[88:89], v[158:159], v[72:73]
	v_fmac_f32_e32 v66, v72, v72
	v_mul_f32_e32 v72, v75, v75
	v_lshlrev_b64 v[92:93], 1, v[98:99]
	v_pk_mul_f32 v[98:99], v[156:157], v[64:65]
	v_fmac_f32_e32 v72, v74, v74
	v_mul_f32_e32 v65, v65, v65
	v_add_f32_e32 v66, v66, v72
	v_fmac_f32_e32 v65, v64, v64
	v_add_f32_e32 v64, v66, v65
	v_add_f32_e32 v64, v67, v64
	v_add_f32_e32 v66, v104, v64
	ds_swizzle_b32 v67, v66 offset:swizzle(SWAP,16)
	v_or_b32_e32 v92, 0x100, v92
	v_pk_mul_f32 v[90:91], v[166:167], v[74:75]
	v_lshl_add_u64 v[64:65], s[44:45], 0, v[92:93]
	v_cvt_pk_bf16_f32 v88, v88, v89
	v_cvt_pk_bf16_f32 v89, v90, v91
	v_cvt_pk_bf16_f32 v90, v98, v99
	v_cvt_pk_bf16_f32 v91, v94, v95
	global_store_dwordx4 v[64:65], v[88:91], off nt
	s_waitcnt lgkmcnt(0)
	v_add_f32_e32 v64, v66, v67
	v_mov_b32_e32 v65, v64
	s_nop 1
	v_permlane32_swap_b32_e32 v64, v65
	s_and_saveexec_b64 s[26:27], s[4:5]
	s_cbranch_execz .LBB0_637
	v_lshl_add_u64 v[66:67], v[96:97], 2, s[50:51]
	v_add_f32_e32 v64, v64, v65
	global_atomic_add_f32 v[66:67], v64, off

.LBB0_638:
	s_nop 0
	v_add_u32_e32 v64, 0x80, v178
	v_ashrrev_i32_e32 v65, 31, v64
	v_lshlrev_b64 v[66:67], 10, v[64:65]
	v_lshl_add_u64 v[66:67], v[66:67], 0, v[176:177]
	v_lshlrev_b64 v[74:75], 2, v[66:67]
	v_lshl_add_u64 v[72:73], s[10:11], 0, v[74:75]
	global_load_dwordx4 v[88:91], v[72:73], off
	global_load_dwordx4 v[92:95], v[72:73], off offset:16
	s_and_b64 vcc, exec, s[8:9]
	v_lshl_add_u64 v[74:75], s[72:73], 0, v[74:75]
	s_waitcnt vmcnt(1)
	v_pk_fma_f32 v[62:63], v[62:63], v[78:79], v[90:91]
	v_pk_fma_f32 v[60:61], v[60:61], v[76:77], v[88:89]
	s_waitcnt vmcnt(0)
	v_pk_fma_f32 v[58:59], v[58:59], v[86:87], v[94:95]
	v_pk_fma_f32 v[56:57], v[56:57], v[84:85], v[92:93]
	v_mov_b32_e32 v88, 0
	global_store_dwordx4 v[74:75], v[60:63], off nt
	global_store_dwordx4 v[74:75], v[56:59], off offset:16 nt
	s_cbranch_vccnz .LBB0_640
	v_pk_mul_f32 v[88:89], v[62:63], v[62:63]
	v_pk_mul_f32 v[90:91], v[60:61], v[60:61]
	v_pk_mul_f32 v[60:61], v[168:169], v[60:61]
	v_pk_mov_b32 v[92:93], v[90:91], v[88:89] op_sel:[1,0]
	v_mov_b32_e32 v91, v89
	v_pk_add_f32 v[88:89], v[92:93], v[90:91]
	v_pk_mul_f32 v[90:91], v[58:59], v[58:59]
	v_pk_mul_f32 v[92:93], v[56:57], v[56:57]
	v_mov_b32_e32 v94, v90
	v_mov_b32_e32 v95, v92
	v_mov_b32_e32 v92, v91
	v_pk_add_f32 v[90:91], v[94:95], v[92:93]
	v_add_f32_e32 v88, v88, v89
	v_add_f32_e32 v88, v88, v91
	v_add_f32_e32 v88, v90, v88
	v_pk_mul_f32 v[90:91], v[174:175], v[58:59]
	v_pk_mul_f32 v[58:59], v[154:155], v[56:57]
	v_cvt_pk_bf16_f32 v56, v60, v61
	v_lshl_add_u64 v[60:61], v[66:67], 1, s[44:45]
	v_pk_mul_f32 v[62:63], v[170:171], v[62:63]
	s_nop 0
	v_cvt_pk_bf16_f32 v57, v62, v63
	v_cvt_pk_bf16_f32 v58, v58, v59
	v_cvt_pk_bf16_f32 v59, v90, v91
	global_store_dwordx4 v[60:61], v[56:59], off nt
.LBB0_640:
	global_load_dwordx4 v[56:59], v[72:73], off offset:512
	s_nop 0
	global_load_dwordx4 v[60:63], v[72:73], off offset:528
	s_and_b64 vcc, exec, s[8:9]
	s_waitcnt vmcnt(1)
	v_pk_fma_f32 v[54:55], v[54:55], v[70:71], v[58:59]
	v_pk_fma_f32 v[52:53], v[52:53], v[68:69], v[56:57]
	s_waitcnt vmcnt(0)
	v_pk_fma_f32 v[50:51], v[50:51], v[82:83], v[62:63]
	v_pk_fma_f32 v[48:49], v[48:49], v[80:81], v[60:61]
	global_store_dwordx4 v[74:75], v[52:55], off offset:512 nt
	global_store_dwordx4 v[74:75], v[48:51], off offset:528 nt
	s_cbranch_vccnz .LBB0_644
	v_pk_mul_f32 v[62:63], v[172:173], v[50:51]
	v_mul_f32_e32 v51, v51, v51
	v_fmac_f32_e32 v51, v50, v50
	v_mul_f32_e32 v50, v53, v53
	v_pk_mul_f32 v[56:57], v[158:159], v[52:53]
	v_fmac_f32_e32 v50, v52, v52
	v_mul_f32_e32 v52, v55, v55
	v_lshlrev_b64 v[60:61], 1, v[66:67]
	v_pk_mul_f32 v[66:67], v[156:157], v[48:49]
	v_fmac_f32_e32 v52, v54, v54
	v_mul_f32_e32 v49, v49, v49
	v_add_f32_e32 v50, v50, v52
	v_fmac_f32_e32 v49, v48, v48
	v_add_f32_e32 v48, v50, v49
	v_add_f32_e32 v48, v51, v48
	v_add_f32_e32 v50, v88, v48
	ds_swizzle_b32 v51, v50 offset:swizzle(SWAP,16)
	v_or_b32_e32 v60, 0x100, v60
	v_pk_mul_f32 v[58:59], v[166:167], v[54:55]
	v_lshl_add_u64 v[48:49], s[44:45], 0, v[60:61]
	v_cvt_pk_bf16_f32 v56, v56, v57
	v_cvt_pk_bf16_f32 v57, v58, v59
	v_cvt_pk_bf16_f32 v58, v66, v67
	v_cvt_pk_bf16_f32 v59, v62, v63
	global_store_dwordx4 v[48:49], v[56:59], off nt
	s_waitcnt lgkmcnt(0)
	v_add_f32_e32 v48, v50, v51
	v_mov_b32_e32 v49, v48
	s_nop 1
	v_permlane32_swap_b32_e32 v48, v49
	s_and_saveexec_b64 s[26:27], s[4:5]
	s_cbranch_execz .LBB0_643
	v_lshl_add_u64 v[50:51], v[64:65], 2, s[50:51]
	v_add_f32_e32 v48, v48, v49
	global_atomic_add_f32 v[50:51], v48, off

.LBB0_644:
	s_nop 0
	v_add_u32_e32 v48, 0x90, v178
	v_ashrrev_i32_e32 v49, 31, v48
	v_lshlrev_b64 v[50:51], 10, v[48:49]
	v_lshl_add_u64 v[50:51], v[50:51], 0, v[176:177]
	v_lshlrev_b64 v[54:55], 2, v[50:51]
	v_lshl_add_u64 v[52:53], s[10:11], 0, v[54:55]
	global_load_dwordx4 v[56:59], v[52:53], off
	global_load_dwordx4 v[60:63], v[52:53], off offset:16
	s_and_b64 vcc, exec, s[8:9]
	v_lshl_add_u64 v[54:55], s[72:73], 0, v[54:55]
	s_waitcnt vmcnt(1)
	v_pk_fma_f32 v[46:47], v[46:47], v[78:79], v[58:59]
	v_pk_fma_f32 v[44:45], v[44:45], v[76:77], v[56:57]
	s_waitcnt vmcnt(0)
	v_pk_fma_f32 v[42:43], v[42:43], v[86:87], v[62:63]
	v_pk_fma_f32 v[40:41], v[40:41], v[84:85], v[60:61]
	v_mov_b32_e32 v56, 0
	global_store_dwordx4 v[54:55], v[44:47], off nt
	global_store_dwordx4 v[54:55], v[40:43], off offset:16 nt
	s_cbranch_vccnz .LBB0_646
	v_pk_mul_f32 v[56:57], v[46:47], v[46:47]
	v_pk_mul_f32 v[58:59], v[44:45], v[44:45]
	v_pk_mul_f32 v[44:45], v[168:169], v[44:45]
	v_pk_mov_b32 v[60:61], v[58:59], v[56:57] op_sel:[1,0]
	v_mov_b32_e32 v59, v57
	v_pk_add_f32 v[56:57], v[60:61], v[58:59]
	v_pk_mul_f32 v[58:59], v[42:43], v[42:43]
	v_pk_mul_f32 v[60:61], v[40:41], v[40:41]
	v_mov_b32_e32 v62, v58
	v_mov_b32_e32 v63, v60
	v_mov_b32_e32 v60, v59
	v_pk_add_f32 v[58:59], v[62:63], v[60:61]
	v_add_f32_e32 v56, v56, v57
	v_add_f32_e32 v56, v56, v59
	v_add_f32_e32 v56, v58, v56
	v_pk_mul_f32 v[58:59], v[174:175], v[42:43]
	v_pk_mul_f32 v[42:43], v[154:155], v[40:41]
	v_cvt_pk_bf16_f32 v40, v44, v45
	v_lshl_add_u64 v[44:45], v[50:51], 1, s[44:45]
	v_pk_mul_f32 v[46:47], v[170:171], v[46:47]
	s_nop 0
	v_cvt_pk_bf16_f32 v41, v46, v47
	v_cvt_pk_bf16_f32 v42, v42, v43
	v_cvt_pk_bf16_f32 v43, v58, v59
	global_store_dwordx4 v[44:45], v[40:43], off nt
.LBB0_646:
	global_load_dwordx4 v[40:43], v[52:53], off offset:512
	s_nop 0
	global_load_dwordx4 v[44:47], v[52:53], off offset:528
	s_and_b64 vcc, exec, s[8:9]
	s_waitcnt vmcnt(1)
	v_pk_fma_f32 v[38:39], v[38:39], v[70:71], v[42:43]
	v_pk_fma_f32 v[36:37], v[36:37], v[68:69], v[40:41]
	s_waitcnt vmcnt(0)
	v_pk_fma_f32 v[34:35], v[34:35], v[82:83], v[46:47]
	v_pk_fma_f32 v[32:33], v[32:33], v[80:81], v[44:45]
	global_store_dwordx4 v[54:55], v[36:39], off offset:512 nt
	global_store_dwordx4 v[54:55], v[32:35], off offset:528 nt
	s_cbranch_vccnz .LBB0_650
	v_pk_mul_f32 v[46:47], v[172:173], v[34:35]
	v_mul_f32_e32 v35, v35, v35
	v_fmac_f32_e32 v35, v34, v34
	v_mul_f32_e32 v34, v37, v37
	v_pk_mul_f32 v[40:41], v[158:159], v[36:37]
	v_fmac_f32_e32 v34, v36, v36
	v_mul_f32_e32 v36, v39, v39
	v_lshlrev_b64 v[44:45], 1, v[50:51]
	v_pk_mul_f32 v[50:51], v[156:157], v[32:33]
	v_fmac_f32_e32 v36, v38, v38
	v_mul_f32_e32 v33, v33, v33
	v_add_f32_e32 v34, v34, v36
	v_fmac_f32_e32 v33, v32, v32
	v_add_f32_e32 v32, v34, v33
	v_add_f32_e32 v32, v35, v32
	v_add_f32_e32 v34, v56, v32
	ds_swizzle_b32 v35, v34 offset:swizzle(SWAP,16)
	v_or_b32_e32 v44, 0x100, v44
	v_pk_mul_f32 v[42:43], v[166:167], v[38:39]
	v_lshl_add_u64 v[32:33], s[44:45], 0, v[44:45]
	v_cvt_pk_bf16_f32 v40, v40, v41
	v_cvt_pk_bf16_f32 v41, v42, v43
	v_cvt_pk_bf16_f32 v42, v50, v51
	v_cvt_pk_bf16_f32 v43, v46, v47
	global_store_dwordx4 v[32:33], v[40:43], off nt
	s_waitcnt lgkmcnt(0)
	v_add_f32_e32 v32, v34, v35
	v_mov_b32_e32 v33, v32
	s_nop 1
	v_permlane32_swap_b32_e32 v32, v33
	s_and_saveexec_b64 s[26:27], s[4:5]
	s_cbranch_execz .LBB0_649
	v_lshl_add_u64 v[34:35], v[48:49], 2, s[50:51]
	v_add_f32_e32 v32, v32, v33
	global_atomic_add_f32 v[34:35], v32, off

.LBB0_650:
	s_nop 0
	v_add_u32_e32 v32, 0xa0, v178
	v_ashrrev_i32_e32 v33, 31, v32
	v_lshlrev_b64 v[34:35], 10, v[32:33]
	v_lshl_add_u64 v[34:35], v[34:35], 0, v[176:177]
	v_lshlrev_b64 v[38:39], 2, v[34:35]
	v_lshl_add_u64 v[36:37], s[10:11], 0, v[38:39]
	global_load_dwordx4 v[40:43], v[36:37], off
	global_load_dwordx4 v[44:47], v[36:37], off offset:16
	s_and_b64 vcc, exec, s[8:9]
	v_lshl_add_u64 v[38:39], s[72:73], 0, v[38:39]
	s_waitcnt vmcnt(1)
	v_pk_fma_f32 v[30:31], v[30:31], v[78:79], v[42:43]
	v_pk_fma_f32 v[28:29], v[28:29], v[76:77], v[40:41]
	s_waitcnt vmcnt(0)
	v_pk_fma_f32 v[26:27], v[26:27], v[86:87], v[46:47]
	v_pk_fma_f32 v[24:25], v[24:25], v[84:85], v[44:45]
	v_mov_b32_e32 v40, 0
	global_store_dwordx4 v[38:39], v[28:31], off nt
	global_store_dwordx4 v[38:39], v[24:27], off offset:16 nt
	s_cbranch_vccnz .LBB0_652
	v_pk_mul_f32 v[40:41], v[30:31], v[30:31]
	v_pk_mul_f32 v[42:43], v[28:29], v[28:29]
	v_pk_mul_f32 v[28:29], v[168:169], v[28:29]
	v_pk_mov_b32 v[44:45], v[42:43], v[40:41] op_sel:[1,0]
	v_mov_b32_e32 v43, v41
	v_pk_add_f32 v[40:41], v[44:45], v[42:43]
	v_pk_mul_f32 v[42:43], v[26:27], v[26:27]
	v_pk_mul_f32 v[44:45], v[24:25], v[24:25]
	v_mov_b32_e32 v46, v42
	v_mov_b32_e32 v47, v44
	v_mov_b32_e32 v44, v43
	v_pk_add_f32 v[42:43], v[46:47], v[44:45]
	v_add_f32_e32 v40, v40, v41
	v_add_f32_e32 v40, v40, v43
	v_add_f32_e32 v40, v42, v40
	v_pk_mul_f32 v[42:43], v[174:175], v[26:27]
	v_pk_mul_f32 v[26:27], v[154:155], v[24:25]
	v_cvt_pk_bf16_f32 v24, v28, v29
	v_lshl_add_u64 v[28:29], v[34:35], 1, s[44:45]
	v_pk_mul_f32 v[30:31], v[170:171], v[30:31]
	s_nop 0
	v_cvt_pk_bf16_f32 v25, v30, v31
	v_cvt_pk_bf16_f32 v26, v26, v27
	v_cvt_pk_bf16_f32 v27, v42, v43
	global_store_dwordx4 v[28:29], v[24:27], off nt
.LBB0_652:
	global_load_dwordx4 v[24:27], v[36:37], off offset:512
	s_nop 0
	global_load_dwordx4 v[28:31], v[36:37], off offset:528
	s_and_b64 vcc, exec, s[8:9]
	s_waitcnt vmcnt(1)
	v_pk_fma_f32 v[22:23], v[22:23], v[70:71], v[26:27]
	v_pk_fma_f32 v[20:21], v[20:21], v[68:69], v[24:25]
	s_waitcnt vmcnt(0)
	v_pk_fma_f32 v[18:19], v[18:19], v[82:83], v[30:31]
	v_pk_fma_f32 v[16:17], v[16:17], v[80:81], v[28:29]
	global_store_dwordx4 v[38:39], v[20:23], off offset:512 nt
	global_store_dwordx4 v[38:39], v[16:19], off offset:528 nt
	s_cbranch_vccnz .LBB0_656
	v_pk_mul_f32 v[30:31], v[172:173], v[18:19]
	v_mul_f32_e32 v19, v19, v19
	v_fmac_f32_e32 v19, v18, v18
	v_mul_f32_e32 v18, v21, v21
	v_pk_mul_f32 v[24:25], v[158:159], v[20:21]
	v_fmac_f32_e32 v18, v20, v20
	v_mul_f32_e32 v20, v23, v23
	v_lshlrev_b64 v[28:29], 1, v[34:35]
	v_pk_mul_f32 v[34:35], v[156:157], v[16:17]
	v_fmac_f32_e32 v20, v22, v22
	v_mul_f32_e32 v17, v17, v17
	v_add_f32_e32 v18, v18, v20
	v_fmac_f32_e32 v17, v16, v16
	v_add_f32_e32 v16, v18, v17
	v_add_f32_e32 v16, v19, v16
	v_add_f32_e32 v18, v40, v16
	ds_swizzle_b32 v19, v18 offset:swizzle(SWAP,16)
	v_or_b32_e32 v28, 0x100, v28
	v_pk_mul_f32 v[26:27], v[166:167], v[22:23]
	v_lshl_add_u64 v[16:17], s[44:45], 0, v[28:29]
	v_cvt_pk_bf16_f32 v24, v24, v25
	v_cvt_pk_bf16_f32 v25, v26, v27
	v_cvt_pk_bf16_f32 v26, v34, v35
	v_cvt_pk_bf16_f32 v27, v30, v31
	global_store_dwordx4 v[16:17], v[24:27], off nt
	s_waitcnt lgkmcnt(0)
	v_add_f32_e32 v16, v18, v19
	v_mov_b32_e32 v17, v16
	s_nop 1
	v_permlane32_swap_b32_e32 v16, v17
	s_and_saveexec_b64 s[26:27], s[4:5]
	s_cbranch_execz .LBB0_655
	v_lshl_add_u64 v[18:19], v[32:33], 2, s[50:51]
	v_add_f32_e32 v16, v16, v17
	global_atomic_add_f32 v[18:19], v16, off

.LBB0_656:
	s_nop 0
	v_add_u32_e32 v16, 0xb0, v178
	v_ashrrev_i32_e32 v17, 31, v16
	v_lshlrev_b64 v[18:19], 10, v[16:17]
	v_lshl_add_u64 v[18:19], v[18:19], 0, v[176:177]
	v_lshlrev_b64 v[22:23], 2, v[18:19]
	v_lshl_add_u64 v[20:21], s[10:11], 0, v[22:23]
	global_load_dwordx4 v[24:27], v[20:21], off
	global_load_dwordx4 v[28:31], v[20:21], off offset:16
	s_and_b64 vcc, exec, s[8:9]
	v_lshl_add_u64 v[22:23], s[72:73], 0, v[22:23]
	s_waitcnt vmcnt(1)
	v_pk_fma_f32 v[14:15], v[14:15], v[78:79], v[26:27]
	v_pk_fma_f32 v[12:13], v[12:13], v[76:77], v[24:25]
	s_waitcnt vmcnt(0)
	v_pk_fma_f32 v[10:11], v[10:11], v[86:87], v[30:31]
	v_pk_fma_f32 v[8:9], v[8:9], v[84:85], v[28:29]
	v_mov_b32_e32 v24, 0
	global_store_dwordx4 v[22:23], v[12:15], off nt
	global_store_dwordx4 v[22:23], v[8:11], off offset:16 nt
	s_cbranch_vccnz .LBB0_658
	v_pk_mul_f32 v[24:25], v[14:15], v[14:15]
	v_pk_mul_f32 v[26:27], v[12:13], v[12:13]
	v_pk_mul_f32 v[12:13], v[168:169], v[12:13]
	v_pk_mov_b32 v[28:29], v[26:27], v[24:25] op_sel:[1,0]
	v_mov_b32_e32 v27, v25
	v_pk_add_f32 v[24:25], v[28:29], v[26:27]
	v_pk_mul_f32 v[26:27], v[10:11], v[10:11]
	v_pk_mul_f32 v[28:29], v[8:9], v[8:9]
	v_mov_b32_e32 v30, v26
	v_mov_b32_e32 v31, v28
	v_mov_b32_e32 v28, v27
	v_pk_add_f32 v[26:27], v[30:31], v[28:29]
	v_add_f32_e32 v24, v24, v25
	v_add_f32_e32 v24, v24, v27
	v_add_f32_e32 v24, v26, v24
	v_pk_mul_f32 v[26:27], v[174:175], v[10:11]
	v_pk_mul_f32 v[10:11], v[154:155], v[8:9]
	v_cvt_pk_bf16_f32 v8, v12, v13
	v_lshl_add_u64 v[12:13], v[18:19], 1, s[44:45]
	v_pk_mul_f32 v[14:15], v[170:171], v[14:15]
	s_nop 0
	v_cvt_pk_bf16_f32 v9, v14, v15
	v_cvt_pk_bf16_f32 v10, v10, v11
	v_cvt_pk_bf16_f32 v11, v26, v27
	global_store_dwordx4 v[12:13], v[8:11], off nt
.LBB0_658:
	global_load_dwordx4 v[8:11], v[20:21], off offset:512
	s_nop 0
	global_load_dwordx4 v[12:15], v[20:21], off offset:528
	s_and_b64 vcc, exec, s[8:9]
	s_waitcnt vmcnt(1)
	v_pk_fma_f32 v[6:7], v[6:7], v[70:71], v[10:11]
	v_pk_fma_f32 v[4:5], v[4:5], v[68:69], v[8:9]
	s_waitcnt vmcnt(0)
	v_pk_fma_f32 v[2:3], v[2:3], v[82:83], v[14:15]
	v_pk_fma_f32 v[0:1], v[0:1], v[80:81], v[12:13]
	global_store_dwordx4 v[22:23], v[4:7], off offset:512 nt
	global_store_dwordx4 v[22:23], v[0:3], off offset:528 nt
	s_cbranch_vccnz .LBB0_662
	v_pk_mul_f32 v[14:15], v[172:173], v[2:3]
	v_mul_f32_e32 v3, v3, v3
	v_fmac_f32_e32 v3, v2, v2
	v_mul_f32_e32 v2, v5, v5
	v_pk_mul_f32 v[8:9], v[158:159], v[4:5]
	v_fmac_f32_e32 v2, v4, v4
	v_mul_f32_e32 v4, v7, v7
	v_lshlrev_b64 v[12:13], 1, v[18:19]
	v_pk_mul_f32 v[18:19], v[156:157], v[0:1]
	v_fmac_f32_e32 v4, v6, v6
	v_mul_f32_e32 v1, v1, v1
	v_add_f32_e32 v2, v2, v4
	v_fmac_f32_e32 v1, v0, v0
	v_add_f32_e32 v0, v2, v1
	v_add_f32_e32 v0, v3, v0
	v_add_f32_e32 v2, v24, v0
	ds_swizzle_b32 v3, v2 offset:swizzle(SWAP,16)
	v_or_b32_e32 v12, 0x100, v12
	v_pk_mul_f32 v[10:11], v[166:167], v[6:7]
	v_lshl_add_u64 v[0:1], s[44:45], 0, v[12:13]
	v_cvt_pk_bf16_f32 v8, v8, v9
	v_cvt_pk_bf16_f32 v9, v10, v11
	v_cvt_pk_bf16_f32 v10, v18, v19
	v_cvt_pk_bf16_f32 v11, v14, v15
	global_store_dwordx4 v[0:1], v[8:11], off nt
	s_waitcnt lgkmcnt(0)
	v_add_f32_e32 v0, v2, v3
	v_mov_b32_e32 v1, v0
	s_nop 1
	v_permlane32_swap_b32_e32 v0, v1
	s_and_saveexec_b64 s[8:9], s[4:5]
	s_cbranch_execz .LBB0_661
	v_lshl_add_u64 v[2:3], v[16:17], 2, s[50:51]
	v_add_f32_e32 v0, v0, v1
	global_atomic_add_f32 v[2:3], v0, off

.LBB0_802:
	v_lshl_add_u32 v178, s56, 8, v184
	v_ashrrev_i32_e32 v179, 31, v178
	v_lshlrev_b64 v[162:163], 10, v[178:179]
	v_lshl_add_u64 v[180:181], v[162:163], 0, v[176:177]
	v_lshl_add_u64 v[182:183], v[180:181], 2, s[72:73]
	global_load_dwordx4 v[188:191], v[182:183], off
	global_load_dwordx4 v[192:195], v[182:183], off offset:16
	s_and_b64 vcc, exec, s[6:7]
	s_waitcnt vmcnt(0)
	v_pk_fma_f32 v[142:143], v[142:143], v[78:79], v[190:191]
	v_pk_fma_f32 v[140:141], v[140:141], v[76:77], v[188:189]
	v_pk_fma_f32 v[138:139], v[138:139], v[86:87], v[194:195]
	v_pk_fma_f32 v[136:137], v[136:137], v[84:85], v[192:193]
	v_mov_b32_e32 v188, 0
	global_store_dwordx4 v[182:183], v[140:143], off nt
	global_store_dwordx4 v[182:183], v[136:139], off offset:16 nt
	s_cbranch_vccnz .LBB0_804
	v_pk_mul_f32 v[162:163], v[142:143], v[142:143]
	v_pk_mul_f32 v[188:189], v[140:141], v[140:141]
	v_pk_mul_f32 v[140:141], v[168:169], v[140:141]
	v_pk_mov_b32 v[190:191], v[188:189], v[162:163] op_sel:[1,0]
	v_mov_b32_e32 v189, v163
	v_pk_add_f32 v[162:163], v[190:191], v[188:189]
	v_pk_mul_f32 v[188:189], v[138:139], v[138:139]
	v_pk_mul_f32 v[190:191], v[136:137], v[136:137]
	v_mov_b32_e32 v192, v188
	v_mov_b32_e32 v193, v190
	v_mov_b32_e32 v190, v189
	v_pk_add_f32 v[188:189], v[192:193], v[190:191]
	v_add_f32_e32 v162, v162, v163
	v_add_f32_e32 v162, v162, v189
	v_add_f32_e32 v188, v188, v162
	v_pk_mul_f32 v[162:163], v[174:175], v[138:139]
	v_pk_mul_f32 v[138:139], v[156:157], v[136:137]
	v_cvt_pk_bf16_f32 v136, v140, v141
	v_lshl_add_u64 v[140:141], v[180:181], 1, s[44:45]
	v_pk_mul_f32 v[142:143], v[170:171], v[142:143]
	s_nop 0
	v_cvt_pk_bf16_f32 v137, v142, v143
	v_cvt_pk_bf16_f32 v138, v138, v139
	v_cvt_pk_bf16_f32 v139, v162, v163
	global_store_dwordx4 v[140:141], v[136:139], off nt
.LBB0_804:
	global_load_dwordx4 v[136:139], v[182:183], off offset:512
	s_nop 0
	global_load_dwordx4 v[140:143], v[182:183], off offset:528
	s_and_b64 vcc, exec, s[6:7]
	s_waitcnt vmcnt(1)
	v_pk_fma_f32 v[134:135], v[134:135], v[74:75], v[138:139]
	v_pk_fma_f32 v[132:133], v[132:133], v[72:73], v[136:137]
	s_waitcnt vmcnt(0)
	v_pk_fma_f32 v[130:131], v[130:131], v[82:83], v[142:143]
	v_pk_fma_f32 v[128:129], v[128:129], v[80:81], v[140:141]
	global_store_dwordx4 v[182:183], v[132:135], off offset:512 nt
	global_store_dwordx4 v[182:183], v[128:131], off offset:528 nt
	s_cbranch_vccnz .LBB0_808
	v_pk_mul_f32 v[142:143], v[172:173], v[130:131]
	v_mul_f32_e32 v131, v131, v131
	v_fmac_f32_e32 v131, v130, v130
	v_mul_f32_e32 v130, v133, v133
	v_pk_mul_f32 v[136:137], v[158:159], v[132:133]
	v_fmac_f32_e32 v130, v132, v132
	v_mul_f32_e32 v132, v135, v135
	v_pk_mul_f32 v[162:163], v[154:155], v[128:129]
	v_fmac_f32_e32 v132, v134, v134
	v_mul_f32_e32 v129, v129, v129
	v_add_f32_e32 v130, v130, v132
	v_fmac_f32_e32 v129, v128, v128
	v_add_f32_e32 v128, v130, v129
	v_add_f32_e32 v128, v131, v128
	v_add_f32_e32 v130, v188, v128
	ds_swizzle_b32 v131, v130 offset:swizzle(SWAP,16)
	v_lshlrev_b64 v[140:141], 1, v[180:181]
	v_or_b32_e32 v140, 0x100, v140
	v_pk_mul_f32 v[138:139], v[166:167], v[134:135]
	v_lshl_add_u64 v[128:129], s[44:45], 0, v[140:141]
	v_cvt_pk_bf16_f32 v136, v136, v137
	v_cvt_pk_bf16_f32 v137, v138, v139
	v_cvt_pk_bf16_f32 v138, v162, v163
	v_cvt_pk_bf16_f32 v139, v142, v143
	global_store_dwordx4 v[128:129], v[136:139], off nt
	s_waitcnt lgkmcnt(0)
	v_add_f32_e32 v128, v130, v131
	v_mov_b32_e32 v129, v128
	s_nop 1
	v_permlane32_swap_b32_e32 v128, v129
	s_and_saveexec_b64 s[24:25], s[2:3]
	s_cbranch_execz .LBB0_807
	v_lshl_add_u64 v[130:131], v[178:179], 2, s[10:11]
	v_add_f32_e32 v128, v128, v129
	global_atomic_add_f32 v[130:131], v128, off

.LBB0_808:
	s_nop 0
	v_or_b32_e32 v128, 16, v178
	v_ashrrev_i32_e32 v129, 31, v128
	v_lshlrev_b64 v[130:131], 10, v[128:129]
	v_lshl_add_u64 v[130:131], v[130:131], 0, v[176:177]
	v_lshl_add_u64 v[132:133], v[130:131], 2, s[72:73]
	global_load_dwordx4 v[134:137], v[132:133], off
	global_load_dwordx4 v[138:141], v[132:133], off offset:16
	s_and_b64 vcc, exec, s[6:7]
	s_waitcnt vmcnt(1)
	v_pk_fma_f32 v[126:127], v[126:127], v[78:79], v[136:137]
	v_pk_fma_f32 v[124:125], v[124:125], v[76:77], v[134:135]
	s_waitcnt vmcnt(0)
	v_pk_fma_f32 v[122:123], v[122:123], v[86:87], v[140:141]
	v_pk_fma_f32 v[120:121], v[120:121], v[84:85], v[138:139]
	v_mov_b32_e32 v134, 0
	global_store_dwordx4 v[132:133], v[124:127], off nt
	global_store_dwordx4 v[132:133], v[120:123], off offset:16 nt
	s_cbranch_vccnz .LBB0_810
	v_pk_mul_f32 v[134:135], v[126:127], v[126:127]
	v_pk_mul_f32 v[136:137], v[124:125], v[124:125]
	v_pk_mul_f32 v[124:125], v[168:169], v[124:125]
	v_pk_mov_b32 v[138:139], v[136:137], v[134:135] op_sel:[1,0]
	v_mov_b32_e32 v137, v135
	v_pk_add_f32 v[134:135], v[138:139], v[136:137]
	v_pk_mul_f32 v[136:137], v[122:123], v[122:123]
	v_pk_mul_f32 v[138:139], v[120:121], v[120:121]
	v_mov_b32_e32 v140, v136
	v_mov_b32_e32 v141, v138
	v_mov_b32_e32 v138, v137
	v_pk_add_f32 v[136:137], v[140:141], v[138:139]
	v_add_f32_e32 v134, v134, v135
	v_add_f32_e32 v134, v134, v137
	v_add_f32_e32 v134, v136, v134
	v_pk_mul_f32 v[136:137], v[174:175], v[122:123]
	v_pk_mul_f32 v[122:123], v[156:157], v[120:121]
	v_cvt_pk_bf16_f32 v120, v124, v125
	v_lshl_add_u64 v[124:125], v[130:131], 1, s[44:45]
	v_pk_mul_f32 v[126:127], v[170:171], v[126:127]
	s_nop 0
	v_cvt_pk_bf16_f32 v121, v126, v127
	v_cvt_pk_bf16_f32 v122, v122, v123
	v_cvt_pk_bf16_f32 v123, v136, v137
	global_store_dwordx4 v[124:125], v[120:123], off nt
.LBB0_810:
	global_load_dwordx4 v[120:123], v[132:133], off offset:512
	s_nop 0
	global_load_dwordx4 v[124:127], v[132:133], off offset:528
	s_and_b64 vcc, exec, s[6:7]
	s_waitcnt vmcnt(1)
	v_pk_fma_f32 v[118:119], v[118:119], v[74:75], v[122:123]
	v_pk_fma_f32 v[116:117], v[116:117], v[72:73], v[120:121]
	s_waitcnt vmcnt(0)
	v_pk_fma_f32 v[114:115], v[114:115], v[82:83], v[126:127]
	v_pk_fma_f32 v[112:113], v[112:113], v[80:81], v[124:125]
	global_store_dwordx4 v[132:133], v[116:119], off offset:512 nt
	global_store_dwordx4 v[132:133], v[112:115], off offset:528 nt
	s_cbranch_vccnz .LBB0_814
	v_pk_mul_f32 v[126:127], v[172:173], v[114:115]
	v_mul_f32_e32 v115, v115, v115
	v_fmac_f32_e32 v115, v114, v114
	v_mul_f32_e32 v114, v117, v117
	v_pk_mul_f32 v[120:121], v[158:159], v[116:117]
	v_fmac_f32_e32 v114, v116, v116
	v_mul_f32_e32 v116, v119, v119
	v_lshlrev_b64 v[124:125], 1, v[130:131]
	v_pk_mul_f32 v[130:131], v[154:155], v[112:113]
	v_fmac_f32_e32 v116, v118, v118
	v_mul_f32_e32 v113, v113, v113
	v_add_f32_e32 v114, v114, v116
	v_fmac_f32_e32 v113, v112, v112
	v_add_f32_e32 v112, v114, v113
	v_add_f32_e32 v112, v115, v112
	v_add_f32_e32 v114, v134, v112
	ds_swizzle_b32 v115, v114 offset:swizzle(SWAP,16)
	v_or_b32_e32 v124, 0x100, v124
	v_pk_mul_f32 v[122:123], v[166:167], v[118:119]
	v_lshl_add_u64 v[112:113], s[44:45], 0, v[124:125]
	v_cvt_pk_bf16_f32 v120, v120, v121
	v_cvt_pk_bf16_f32 v121, v122, v123
	v_cvt_pk_bf16_f32 v122, v130, v131
	v_cvt_pk_bf16_f32 v123, v126, v127
	global_store_dwordx4 v[112:113], v[120:123], off nt
	s_waitcnt lgkmcnt(0)
	v_add_f32_e32 v112, v114, v115
	v_mov_b32_e32 v113, v112
	s_nop 1
	v_permlane32_swap_b32_e32 v112, v113
	s_and_saveexec_b64 s[24:25], s[2:3]
	s_cbranch_execz .LBB0_813
	v_lshl_add_u64 v[114:115], v[128:129], 2, s[10:11]
	v_add_f32_e32 v112, v112, v113
	global_atomic_add_f32 v[114:115], v112, off

.LBB0_814:
	s_nop 0
	v_or_b32_e32 v112, 32, v178
	v_ashrrev_i32_e32 v113, 31, v112
	v_lshlrev_b64 v[114:115], 10, v[112:113]
	v_lshl_add_u64 v[114:115], v[114:115], 0, v[176:177]
	v_lshl_add_u64 v[116:117], v[114:115], 2, s[72:73]
	global_load_dwordx4 v[118:121], v[116:117], off
	global_load_dwordx4 v[122:125], v[116:117], off offset:16
	s_and_b64 vcc, exec, s[6:7]
	s_waitcnt vmcnt(1)
	v_pk_fma_f32 v[110:111], v[110:111], v[78:79], v[120:121]
	v_pk_fma_f32 v[108:109], v[108:109], v[76:77], v[118:119]
	s_waitcnt vmcnt(0)
	v_pk_fma_f32 v[106:107], v[106:107], v[86:87], v[124:125]
	v_pk_fma_f32 v[104:105], v[104:105], v[84:85], v[122:123]
	v_mov_b32_e32 v118, 0
	global_store_dwordx4 v[116:117], v[108:111], off nt
	global_store_dwordx4 v[116:117], v[104:107], off offset:16 nt
	s_cbranch_vccnz .LBB0_816
	v_pk_mul_f32 v[118:119], v[110:111], v[110:111]
	v_pk_mul_f32 v[120:121], v[108:109], v[108:109]
	v_pk_mul_f32 v[108:109], v[168:169], v[108:109]
	v_pk_mov_b32 v[122:123], v[120:121], v[118:119] op_sel:[1,0]
	v_mov_b32_e32 v121, v119
	v_pk_add_f32 v[118:119], v[122:123], v[120:121]
	v_pk_mul_f32 v[120:121], v[106:107], v[106:107]
	v_pk_mul_f32 v[122:123], v[104:105], v[104:105]
	v_mov_b32_e32 v124, v120
	v_mov_b32_e32 v125, v122
	v_mov_b32_e32 v122, v121
	v_pk_add_f32 v[120:121], v[124:125], v[122:123]
	v_add_f32_e32 v118, v118, v119
	v_add_f32_e32 v118, v118, v121
	v_add_f32_e32 v118, v120, v118
	v_pk_mul_f32 v[120:121], v[174:175], v[106:107]
	v_pk_mul_f32 v[106:107], v[156:157], v[104:105]
	v_cvt_pk_bf16_f32 v104, v108, v109
	v_lshl_add_u64 v[108:109], v[114:115], 1, s[44:45]
	v_pk_mul_f32 v[110:111], v[170:171], v[110:111]
	s_nop 0
	v_cvt_pk_bf16_f32 v105, v110, v111
	v_cvt_pk_bf16_f32 v106, v106, v107
	v_cvt_pk_bf16_f32 v107, v120, v121
	global_store_dwordx4 v[108:109], v[104:107], off nt
.LBB0_816:
	global_load_dwordx4 v[104:107], v[116:117], off offset:512
	s_nop 0
	global_load_dwordx4 v[108:111], v[116:117], off offset:528
	s_and_b64 vcc, exec, s[6:7]
	s_waitcnt vmcnt(1)
	v_pk_fma_f32 v[102:103], v[102:103], v[74:75], v[106:107]
	v_pk_fma_f32 v[100:101], v[100:101], v[72:73], v[104:105]
	s_waitcnt vmcnt(0)
	v_pk_fma_f32 v[98:99], v[98:99], v[82:83], v[110:111]
	v_pk_fma_f32 v[96:97], v[96:97], v[80:81], v[108:109]
	global_store_dwordx4 v[116:117], v[100:103], off offset:512 nt
	global_store_dwordx4 v[116:117], v[96:99], off offset:528 nt
	s_cbranch_vccnz .LBB0_820
	v_pk_mul_f32 v[110:111], v[172:173], v[98:99]
	v_mul_f32_e32 v99, v99, v99
	v_fmac_f32_e32 v99, v98, v98
	v_mul_f32_e32 v98, v101, v101
	v_pk_mul_f32 v[104:105], v[158:159], v[100:101]
	v_fmac_f32_e32 v98, v100, v100
	v_mul_f32_e32 v100, v103, v103
	v_lshlrev_b64 v[108:109], 1, v[114:115]
	v_pk_mul_f32 v[114:115], v[154:155], v[96:97]
	v_fmac_f32_e32 v100, v102, v102
	v_mul_f32_e32 v97, v97, v97
	v_add_f32_e32 v98, v98, v100
	v_fmac_f32_e32 v97, v96, v96
	v_add_f32_e32 v96, v98, v97
	v_add_f32_e32 v96, v99, v96
	v_add_f32_e32 v98, v118, v96
	ds_swizzle_b32 v99, v98 offset:swizzle(SWAP,16)
	v_or_b32_e32 v108, 0x100, v108
	v_pk_mul_f32 v[106:107], v[166:167], v[102:103]
	v_lshl_add_u64 v[96:97], s[44:45], 0, v[108:109]
	v_cvt_pk_bf16_f32 v104, v104, v105
	v_cvt_pk_bf16_f32 v105, v106, v107
	v_cvt_pk_bf16_f32 v106, v114, v115
	v_cvt_pk_bf16_f32 v107, v110, v111
	global_store_dwordx4 v[96:97], v[104:107], off nt
	s_waitcnt lgkmcnt(0)
	v_add_f32_e32 v96, v98, v99
	v_mov_b32_e32 v97, v96
	s_nop 1
	v_permlane32_swap_b32_e32 v96, v97
	s_and_saveexec_b64 s[24:25], s[2:3]
	s_cbranch_execz .LBB0_819
	v_lshl_add_u64 v[98:99], v[112:113], 2, s[10:11]
	v_add_f32_e32 v96, v96, v97
	global_atomic_add_f32 v[98:99], v96, off

.LBB0_820:
	s_nop 0
	v_or_b32_e32 v96, 48, v178
	v_ashrrev_i32_e32 v97, 31, v96
	v_lshlrev_b64 v[98:99], 10, v[96:97]
	v_lshl_add_u64 v[98:99], v[98:99], 0, v[176:177]
	v_lshl_add_u64 v[100:101], v[98:99], 2, s[72:73]
	global_load_dwordx4 v[102:105], v[100:101], off
	global_load_dwordx4 v[106:109], v[100:101], off offset:16
	s_and_b64 vcc, exec, s[6:7]
	s_waitcnt vmcnt(1)
	v_pk_fma_f32 v[94:95], v[94:95], v[78:79], v[104:105]
	v_pk_fma_f32 v[92:93], v[92:93], v[76:77], v[102:103]
	s_waitcnt vmcnt(0)
	v_pk_fma_f32 v[90:91], v[90:91], v[86:87], v[108:109]
	v_pk_fma_f32 v[88:89], v[88:89], v[84:85], v[106:107]
	v_mov_b32_e32 v102, 0
	global_store_dwordx4 v[100:101], v[92:95], off nt
	global_store_dwordx4 v[100:101], v[88:91], off offset:16 nt
	s_cbranch_vccnz .LBB0_822
	v_pk_mul_f32 v[102:103], v[94:95], v[94:95]
	v_pk_mul_f32 v[104:105], v[92:93], v[92:93]
	v_pk_mul_f32 v[92:93], v[168:169], v[92:93]
	v_pk_mov_b32 v[106:107], v[104:105], v[102:103] op_sel:[1,0]
	v_mov_b32_e32 v105, v103
	v_pk_add_f32 v[102:103], v[106:107], v[104:105]
	v_pk_mul_f32 v[104:105], v[90:91], v[90:91]
	v_pk_mul_f32 v[106:107], v[88:89], v[88:89]
	v_mov_b32_e32 v108, v104
	v_mov_b32_e32 v109, v106
	v_mov_b32_e32 v106, v105
	v_pk_add_f32 v[104:105], v[108:109], v[106:107]
	v_add_f32_e32 v102, v102, v103
	v_add_f32_e32 v102, v102, v105
	v_add_f32_e32 v102, v104, v102
	v_pk_mul_f32 v[104:105], v[174:175], v[90:91]
	v_pk_mul_f32 v[90:91], v[156:157], v[88:89]
	v_cvt_pk_bf16_f32 v88, v92, v93
	v_lshl_add_u64 v[92:93], v[98:99], 1, s[44:45]
	v_pk_mul_f32 v[94:95], v[170:171], v[94:95]
	s_nop 0
	v_cvt_pk_bf16_f32 v89, v94, v95
	v_cvt_pk_bf16_f32 v90, v90, v91
	v_cvt_pk_bf16_f32 v91, v104, v105
	global_store_dwordx4 v[92:93], v[88:91], off nt
.LBB0_822:
	global_load_dwordx4 v[88:91], v[100:101], off offset:512
	s_nop 0
	global_load_dwordx4 v[92:95], v[100:101], off offset:528
	s_and_b64 vcc, exec, s[6:7]
	s_waitcnt vmcnt(1)
	v_pk_fma_f32 v[70:71], v[70:71], v[74:75], v[90:91]
	v_pk_fma_f32 v[68:69], v[68:69], v[72:73], v[88:89]
	s_waitcnt vmcnt(0)
	v_pk_fma_f32 v[66:67], v[66:67], v[82:83], v[94:95]
	v_pk_fma_f32 v[64:65], v[64:65], v[80:81], v[92:93]
	global_store_dwordx4 v[100:101], v[68:71], off offset:512 nt
	global_store_dwordx4 v[100:101], v[64:67], off offset:528 nt
	s_cbranch_vccnz .LBB0_826
	v_pk_mul_f32 v[94:95], v[172:173], v[66:67]
	v_mul_f32_e32 v67, v67, v67
	v_fmac_f32_e32 v67, v66, v66
	v_mul_f32_e32 v66, v69, v69
	v_pk_mul_f32 v[88:89], v[158:159], v[68:69]
	v_fmac_f32_e32 v66, v68, v68
	v_mul_f32_e32 v68, v71, v71
	v_lshlrev_b64 v[92:93], 1, v[98:99]
	v_pk_mul_f32 v[98:99], v[154:155], v[64:65]
	v_fmac_f32_e32 v68, v70, v70
	v_mul_f32_e32 v65, v65, v65
	v_add_f32_e32 v66, v66, v68
	v_fmac_f32_e32 v65, v64, v64
	v_add_f32_e32 v64, v66, v65
	v_add_f32_e32 v64, v67, v64
	v_add_f32_e32 v66, v102, v64
	ds_swizzle_b32 v67, v66 offset:swizzle(SWAP,16)
	v_or_b32_e32 v92, 0x100, v92
	v_pk_mul_f32 v[90:91], v[166:167], v[70:71]
	v_lshl_add_u64 v[64:65], s[44:45], 0, v[92:93]
	v_cvt_pk_bf16_f32 v88, v88, v89
	v_cvt_pk_bf16_f32 v89, v90, v91
	v_cvt_pk_bf16_f32 v90, v98, v99
	v_cvt_pk_bf16_f32 v91, v94, v95
	global_store_dwordx4 v[64:65], v[88:91], off nt
	s_waitcnt lgkmcnt(0)
	v_add_f32_e32 v64, v66, v67
	v_mov_b32_e32 v65, v64
	s_nop 1
	v_permlane32_swap_b32_e32 v64, v65
	s_and_saveexec_b64 s[24:25], s[2:3]
	s_cbranch_execz .LBB0_825
	v_lshl_add_u64 v[66:67], v[96:97], 2, s[10:11]
	v_add_f32_e32 v64, v64, v65
	global_atomic_add_f32 v[66:67], v64, off

.LBB0_826:
	s_nop 0
	v_add_u32_e32 v64, 0x80, v178
	v_ashrrev_i32_e32 v65, 31, v64
	v_lshlrev_b64 v[66:67], 10, v[64:65]
	v_lshl_add_u64 v[66:67], v[66:67], 0, v[176:177]
	v_lshl_add_u64 v[68:69], v[66:67], 2, s[72:73]
	global_load_dwordx4 v[88:91], v[68:69], off
	global_load_dwordx4 v[92:95], v[68:69], off offset:16
	s_and_b64 vcc, exec, s[6:7]
	v_mov_b32_e32 v70, 0
	s_waitcnt vmcnt(1)
	v_pk_fma_f32 v[62:63], v[62:63], v[78:79], v[90:91]
	v_pk_fma_f32 v[60:61], v[60:61], v[76:77], v[88:89]
	s_waitcnt vmcnt(0)
	v_pk_fma_f32 v[58:59], v[58:59], v[86:87], v[94:95]
	v_pk_fma_f32 v[56:57], v[56:57], v[84:85], v[92:93]
	global_store_dwordx4 v[68:69], v[60:63], off nt
	global_store_dwordx4 v[68:69], v[56:59], off offset:16 nt
	s_cbranch_vccnz .LBB0_828
	v_pk_mul_f32 v[70:71], v[62:63], v[62:63]
	v_pk_mul_f32 v[88:89], v[60:61], v[60:61]
	v_pk_mul_f32 v[60:61], v[168:169], v[60:61]
	v_pk_mov_b32 v[90:91], v[88:89], v[70:71] op_sel:[1,0]
	v_mov_b32_e32 v89, v71
	v_pk_add_f32 v[70:71], v[90:91], v[88:89]
	v_pk_mul_f32 v[88:89], v[58:59], v[58:59]
	v_pk_mul_f32 v[90:91], v[56:57], v[56:57]
	v_mov_b32_e32 v92, v88
	v_mov_b32_e32 v93, v90
	v_mov_b32_e32 v90, v89
	v_pk_add_f32 v[88:89], v[92:93], v[90:91]
	v_add_f32_e32 v70, v70, v71
	v_add_f32_e32 v70, v70, v89
	v_add_f32_e32 v70, v88, v70
	v_pk_mul_f32 v[88:89], v[174:175], v[58:59]
	v_pk_mul_f32 v[58:59], v[156:157], v[56:57]
	v_cvt_pk_bf16_f32 v56, v60, v61
	v_lshl_add_u64 v[60:61], v[66:67], 1, s[44:45]
	v_pk_mul_f32 v[62:63], v[170:171], v[62:63]
	s_nop 0
	v_cvt_pk_bf16_f32 v57, v62, v63
	v_cvt_pk_bf16_f32 v58, v58, v59
	v_cvt_pk_bf16_f32 v59, v88, v89
	global_store_dwordx4 v[60:61], v[56:59], off nt
.LBB0_828:
	global_load_dwordx4 v[56:59], v[68:69], off offset:512
	s_nop 0
	global_load_dwordx4 v[60:63], v[68:69], off offset:528
	s_and_b64 vcc, exec, s[6:7]
	s_waitcnt vmcnt(1)
	v_pk_fma_f32 v[54:55], v[54:55], v[74:75], v[58:59]
	v_pk_fma_f32 v[52:53], v[52:53], v[72:73], v[56:57]
	s_waitcnt vmcnt(0)
	v_pk_fma_f32 v[50:51], v[50:51], v[82:83], v[62:63]
	v_pk_fma_f32 v[48:49], v[48:49], v[80:81], v[60:61]
	global_store_dwordx4 v[68:69], v[52:55], off offset:512 nt
	global_store_dwordx4 v[68:69], v[48:51], off offset:528 nt
	s_cbranch_vccnz .LBB0_832
	v_pk_mul_f32 v[62:63], v[172:173], v[50:51]
	v_mul_f32_e32 v51, v51, v51
	v_fmac_f32_e32 v51, v50, v50
	v_mul_f32_e32 v50, v53, v53
	v_pk_mul_f32 v[56:57], v[158:159], v[52:53]
	v_fmac_f32_e32 v50, v52, v52
	v_mul_f32_e32 v52, v55, v55
	v_lshlrev_b64 v[60:61], 1, v[66:67]
	v_pk_mul_f32 v[66:67], v[154:155], v[48:49]
	v_fmac_f32_e32 v52, v54, v54
	v_mul_f32_e32 v49, v49, v49
	v_add_f32_e32 v50, v50, v52
	v_fmac_f32_e32 v49, v48, v48
	v_add_f32_e32 v48, v50, v49
	v_add_f32_e32 v48, v51, v48
	v_add_f32_e32 v50, v70, v48
	ds_swizzle_b32 v51, v50 offset:swizzle(SWAP,16)
	v_or_b32_e32 v60, 0x100, v60
	v_pk_mul_f32 v[58:59], v[166:167], v[54:55]
	v_lshl_add_u64 v[48:49], s[44:45], 0, v[60:61]
	v_cvt_pk_bf16_f32 v56, v56, v57
	v_cvt_pk_bf16_f32 v57, v58, v59
	v_cvt_pk_bf16_f32 v58, v66, v67
	v_cvt_pk_bf16_f32 v59, v62, v63
	global_store_dwordx4 v[48:49], v[56:59], off nt
	s_waitcnt lgkmcnt(0)
	v_add_f32_e32 v48, v50, v51
	v_mov_b32_e32 v49, v48
	s_nop 1
	v_permlane32_swap_b32_e32 v48, v49
	s_and_saveexec_b64 s[24:25], s[2:3]
	s_cbranch_execz .LBB0_831
	v_lshl_add_u64 v[50:51], v[64:65], 2, s[10:11]
	v_add_f32_e32 v48, v48, v49
	global_atomic_add_f32 v[50:51], v48, off

.LBB0_832:
	s_nop 0
	v_add_u32_e32 v48, 0x90, v178
	v_ashrrev_i32_e32 v49, 31, v48
	v_lshlrev_b64 v[50:51], 10, v[48:49]
	v_lshl_add_u64 v[50:51], v[50:51], 0, v[176:177]
	v_lshl_add_u64 v[52:53], v[50:51], 2, s[72:73]
	global_load_dwordx4 v[54:57], v[52:53], off
	global_load_dwordx4 v[58:61], v[52:53], off offset:16
	s_and_b64 vcc, exec, s[6:7]
	s_waitcnt vmcnt(1)
	v_pk_fma_f32 v[46:47], v[46:47], v[78:79], v[56:57]
	v_pk_fma_f32 v[44:45], v[44:45], v[76:77], v[54:55]
	s_waitcnt vmcnt(0)
	v_pk_fma_f32 v[42:43], v[42:43], v[86:87], v[60:61]
	v_pk_fma_f32 v[40:41], v[40:41], v[84:85], v[58:59]
	v_mov_b32_e32 v54, 0
	global_store_dwordx4 v[52:53], v[44:47], off nt
	global_store_dwordx4 v[52:53], v[40:43], off offset:16 nt
	s_cbranch_vccnz .LBB0_834
	v_pk_mul_f32 v[54:55], v[46:47], v[46:47]
	v_pk_mul_f32 v[56:57], v[44:45], v[44:45]
	v_pk_mul_f32 v[44:45], v[168:169], v[44:45]
	v_pk_mov_b32 v[58:59], v[56:57], v[54:55] op_sel:[1,0]
	v_mov_b32_e32 v57, v55
	v_pk_add_f32 v[54:55], v[58:59], v[56:57]
	v_pk_mul_f32 v[56:57], v[42:43], v[42:43]
	v_pk_mul_f32 v[58:59], v[40:41], v[40:41]
	v_mov_b32_e32 v60, v56
	v_mov_b32_e32 v61, v58
	v_mov_b32_e32 v58, v57
	v_pk_add_f32 v[56:57], v[60:61], v[58:59]
	v_add_f32_e32 v54, v54, v55
	v_add_f32_e32 v54, v54, v57
	v_add_f32_e32 v54, v56, v54
	v_pk_mul_f32 v[56:57], v[174:175], v[42:43]
	v_pk_mul_f32 v[42:43], v[156:157], v[40:41]
	v_cvt_pk_bf16_f32 v40, v44, v45
	v_lshl_add_u64 v[44:45], v[50:51], 1, s[44:45]
	v_pk_mul_f32 v[46:47], v[170:171], v[46:47]
	s_nop 0
	v_cvt_pk_bf16_f32 v41, v46, v47
	v_cvt_pk_bf16_f32 v42, v42, v43
	v_cvt_pk_bf16_f32 v43, v56, v57
	global_store_dwordx4 v[44:45], v[40:43], off nt
.LBB0_834:
	global_load_dwordx4 v[40:43], v[52:53], off offset:512
	s_nop 0
	global_load_dwordx4 v[44:47], v[52:53], off offset:528
	s_and_b64 vcc, exec, s[6:7]
	s_waitcnt vmcnt(1)
	v_pk_fma_f32 v[38:39], v[38:39], v[74:75], v[42:43]
	v_pk_fma_f32 v[36:37], v[36:37], v[72:73], v[40:41]
	s_waitcnt vmcnt(0)
	v_pk_fma_f32 v[34:35], v[34:35], v[82:83], v[46:47]
	v_pk_fma_f32 v[32:33], v[32:33], v[80:81], v[44:45]
	global_store_dwordx4 v[52:53], v[36:39], off offset:512 nt
	global_store_dwordx4 v[52:53], v[32:35], off offset:528 nt
	s_cbranch_vccnz .LBB0_838
	v_pk_mul_f32 v[46:47], v[172:173], v[34:35]
	v_mul_f32_e32 v35, v35, v35
	v_fmac_f32_e32 v35, v34, v34
	v_mul_f32_e32 v34, v37, v37
	v_pk_mul_f32 v[40:41], v[158:159], v[36:37]
	v_fmac_f32_e32 v34, v36, v36
	v_mul_f32_e32 v36, v39, v39
	v_lshlrev_b64 v[44:45], 1, v[50:51]
	v_pk_mul_f32 v[50:51], v[154:155], v[32:33]
	v_fmac_f32_e32 v36, v38, v38
	v_mul_f32_e32 v33, v33, v33
	v_add_f32_e32 v34, v34, v36
	v_fmac_f32_e32 v33, v32, v32
	v_add_f32_e32 v32, v34, v33
	v_add_f32_e32 v32, v35, v32
	v_add_f32_e32 v34, v54, v32
	ds_swizzle_b32 v35, v34 offset:swizzle(SWAP,16)
	v_or_b32_e32 v44, 0x100, v44
	v_pk_mul_f32 v[42:43], v[166:167], v[38:39]
	v_lshl_add_u64 v[32:33], s[44:45], 0, v[44:45]
	v_cvt_pk_bf16_f32 v40, v40, v41
	v_cvt_pk_bf16_f32 v41, v42, v43
	v_cvt_pk_bf16_f32 v42, v50, v51
	v_cvt_pk_bf16_f32 v43, v46, v47
	global_store_dwordx4 v[32:33], v[40:43], off nt
	s_waitcnt lgkmcnt(0)
	v_add_f32_e32 v32, v34, v35
	v_mov_b32_e32 v33, v32
	s_nop 1
	v_permlane32_swap_b32_e32 v32, v33
	s_and_saveexec_b64 s[24:25], s[2:3]
	s_cbranch_execz .LBB0_837
	v_lshl_add_u64 v[34:35], v[48:49], 2, s[10:11]
	v_add_f32_e32 v32, v32, v33
	global_atomic_add_f32 v[34:35], v32, off

.LBB0_838:
	s_nop 0
	v_add_u32_e32 v32, 0xa0, v178
	v_ashrrev_i32_e32 v33, 31, v32
	v_lshlrev_b64 v[34:35], 10, v[32:33]
	v_lshl_add_u64 v[34:35], v[34:35], 0, v[176:177]
	v_lshl_add_u64 v[36:37], v[34:35], 2, s[72:73]
	global_load_dwordx4 v[38:41], v[36:37], off
	global_load_dwordx4 v[42:45], v[36:37], off offset:16
	s_and_b64 vcc, exec, s[6:7]
	s_waitcnt vmcnt(1)
	v_pk_fma_f32 v[30:31], v[30:31], v[78:79], v[40:41]
	v_pk_fma_f32 v[28:29], v[28:29], v[76:77], v[38:39]
	s_waitcnt vmcnt(0)
	v_pk_fma_f32 v[26:27], v[26:27], v[86:87], v[44:45]
	v_pk_fma_f32 v[24:25], v[24:25], v[84:85], v[42:43]
	v_mov_b32_e32 v38, 0
	global_store_dwordx4 v[36:37], v[28:31], off nt
	global_store_dwordx4 v[36:37], v[24:27], off offset:16 nt
	s_cbranch_vccnz .LBB0_840
	v_pk_mul_f32 v[38:39], v[30:31], v[30:31]
	v_pk_mul_f32 v[40:41], v[28:29], v[28:29]
	v_pk_mul_f32 v[28:29], v[168:169], v[28:29]
	v_pk_mov_b32 v[42:43], v[40:41], v[38:39] op_sel:[1,0]
	v_mov_b32_e32 v41, v39
	v_pk_add_f32 v[38:39], v[42:43], v[40:41]
	v_pk_mul_f32 v[40:41], v[26:27], v[26:27]
	v_pk_mul_f32 v[42:43], v[24:25], v[24:25]
	v_mov_b32_e32 v44, v40
	v_mov_b32_e32 v45, v42
	v_mov_b32_e32 v42, v41
	v_pk_add_f32 v[40:41], v[44:45], v[42:43]
	v_add_f32_e32 v38, v38, v39
	v_add_f32_e32 v38, v38, v41
	v_add_f32_e32 v38, v40, v38
	v_pk_mul_f32 v[40:41], v[174:175], v[26:27]
	v_pk_mul_f32 v[26:27], v[156:157], v[24:25]
	v_cvt_pk_bf16_f32 v24, v28, v29
	v_lshl_add_u64 v[28:29], v[34:35], 1, s[44:45]
	v_pk_mul_f32 v[30:31], v[170:171], v[30:31]
	s_nop 0
	v_cvt_pk_bf16_f32 v25, v30, v31
	v_cvt_pk_bf16_f32 v26, v26, v27
	v_cvt_pk_bf16_f32 v27, v40, v41
	global_store_dwordx4 v[28:29], v[24:27], off nt
.LBB0_840:
	global_load_dwordx4 v[24:27], v[36:37], off offset:512
	s_nop 0
	global_load_dwordx4 v[28:31], v[36:37], off offset:528
	s_and_b64 vcc, exec, s[6:7]
	s_waitcnt vmcnt(1)
	v_pk_fma_f32 v[22:23], v[22:23], v[74:75], v[26:27]
	v_pk_fma_f32 v[20:21], v[20:21], v[72:73], v[24:25]
	s_waitcnt vmcnt(0)
	v_pk_fma_f32 v[18:19], v[18:19], v[82:83], v[30:31]
	v_pk_fma_f32 v[16:17], v[16:17], v[80:81], v[28:29]
	global_store_dwordx4 v[36:37], v[20:23], off offset:512 nt
	global_store_dwordx4 v[36:37], v[16:19], off offset:528 nt
	s_cbranch_vccnz .LBB0_844
	v_pk_mul_f32 v[30:31], v[172:173], v[18:19]
	v_mul_f32_e32 v19, v19, v19
	v_fmac_f32_e32 v19, v18, v18
	v_mul_f32_e32 v18, v21, v21
	v_pk_mul_f32 v[24:25], v[158:159], v[20:21]
	v_fmac_f32_e32 v18, v20, v20
	v_mul_f32_e32 v20, v23, v23
	v_lshlrev_b64 v[28:29], 1, v[34:35]
	v_pk_mul_f32 v[34:35], v[154:155], v[16:17]
	v_fmac_f32_e32 v20, v22, v22
	v_mul_f32_e32 v17, v17, v17
	v_add_f32_e32 v18, v18, v20
	v_fmac_f32_e32 v17, v16, v16
	v_add_f32_e32 v16, v18, v17
	v_add_f32_e32 v16, v19, v16
	v_add_f32_e32 v18, v38, v16
	ds_swizzle_b32 v19, v18 offset:swizzle(SWAP,16)
	v_or_b32_e32 v28, 0x100, v28
	v_pk_mul_f32 v[26:27], v[166:167], v[22:23]
	v_lshl_add_u64 v[16:17], s[44:45], 0, v[28:29]
	v_cvt_pk_bf16_f32 v24, v24, v25
	v_cvt_pk_bf16_f32 v25, v26, v27
	v_cvt_pk_bf16_f32 v26, v34, v35
	v_cvt_pk_bf16_f32 v27, v30, v31
	global_store_dwordx4 v[16:17], v[24:27], off nt
	s_waitcnt lgkmcnt(0)
	v_add_f32_e32 v16, v18, v19
	v_mov_b32_e32 v17, v16
	s_nop 1
	v_permlane32_swap_b32_e32 v16, v17
	s_and_saveexec_b64 s[24:25], s[2:3]
	s_cbranch_execz .LBB0_843
	v_lshl_add_u64 v[18:19], v[32:33], 2, s[10:11]
	v_add_f32_e32 v16, v16, v17
	global_atomic_add_f32 v[18:19], v16, off

.LBB0_844:
	s_nop 0
	v_add_u32_e32 v16, 0xb0, v178
	v_ashrrev_i32_e32 v17, 31, v16
	v_lshlrev_b64 v[18:19], 10, v[16:17]
	v_lshl_add_u64 v[18:19], v[18:19], 0, v[176:177]
	v_lshl_add_u64 v[20:21], v[18:19], 2, s[72:73]
	global_load_dwordx4 v[22:25], v[20:21], off
	global_load_dwordx4 v[26:29], v[20:21], off offset:16
	s_and_b64 vcc, exec, s[6:7]
	s_waitcnt vmcnt(1)
	v_pk_fma_f32 v[14:15], v[14:15], v[78:79], v[24:25]
	v_pk_fma_f32 v[12:13], v[12:13], v[76:77], v[22:23]
	s_waitcnt vmcnt(0)
	v_pk_fma_f32 v[10:11], v[10:11], v[86:87], v[28:29]
	v_pk_fma_f32 v[8:9], v[8:9], v[84:85], v[26:27]
	v_mov_b32_e32 v22, 0
	global_store_dwordx4 v[20:21], v[12:15], off nt
	global_store_dwordx4 v[20:21], v[8:11], off offset:16 nt
	s_cbranch_vccnz .LBB0_846
	v_pk_mul_f32 v[22:23], v[14:15], v[14:15]
	v_pk_mul_f32 v[24:25], v[12:13], v[12:13]
	v_pk_mul_f32 v[12:13], v[168:169], v[12:13]
	v_pk_mov_b32 v[26:27], v[24:25], v[22:23] op_sel:[1,0]
	v_mov_b32_e32 v25, v23
	v_pk_add_f32 v[22:23], v[26:27], v[24:25]
	v_pk_mul_f32 v[24:25], v[10:11], v[10:11]
	v_pk_mul_f32 v[26:27], v[8:9], v[8:9]
	v_mov_b32_e32 v28, v24
	v_mov_b32_e32 v29, v26
	v_mov_b32_e32 v26, v25
	v_pk_add_f32 v[24:25], v[28:29], v[26:27]
	v_add_f32_e32 v22, v22, v23
	v_add_f32_e32 v22, v22, v25
	v_add_f32_e32 v22, v24, v22
	v_pk_mul_f32 v[24:25], v[174:175], v[10:11]
	v_pk_mul_f32 v[10:11], v[156:157], v[8:9]
	v_cvt_pk_bf16_f32 v8, v12, v13
	v_lshl_add_u64 v[12:13], v[18:19], 1, s[44:45]
	v_pk_mul_f32 v[14:15], v[170:171], v[14:15]
	s_nop 0
	v_cvt_pk_bf16_f32 v9, v14, v15
	v_cvt_pk_bf16_f32 v10, v10, v11
	v_cvt_pk_bf16_f32 v11, v24, v25
	global_store_dwordx4 v[12:13], v[8:11], off nt
.LBB0_846:
	global_load_dwordx4 v[8:11], v[20:21], off offset:512
	s_nop 0
	global_load_dwordx4 v[12:15], v[20:21], off offset:528
	s_and_b64 vcc, exec, s[6:7]
	s_waitcnt vmcnt(1)
	v_pk_fma_f32 v[6:7], v[6:7], v[74:75], v[10:11]
	v_pk_fma_f32 v[4:5], v[4:5], v[72:73], v[8:9]
	s_waitcnt vmcnt(0)
	v_pk_fma_f32 v[2:3], v[2:3], v[82:83], v[14:15]
	v_pk_fma_f32 v[0:1], v[0:1], v[80:81], v[12:13]
	global_store_dwordx4 v[20:21], v[4:7], off offset:512 nt
	global_store_dwordx4 v[20:21], v[0:3], off offset:528 nt
	s_cbranch_vccnz .LBB0_850
	v_pk_mul_f32 v[14:15], v[172:173], v[2:3]
	v_mul_f32_e32 v3, v3, v3
	v_fmac_f32_e32 v3, v2, v2
	v_mul_f32_e32 v2, v5, v5
	v_pk_mul_f32 v[8:9], v[158:159], v[4:5]
	v_fmac_f32_e32 v2, v4, v4
	v_mul_f32_e32 v4, v7, v7
	v_lshlrev_b64 v[12:13], 1, v[18:19]
	v_pk_mul_f32 v[18:19], v[154:155], v[0:1]
	v_fmac_f32_e32 v4, v6, v6
	v_mul_f32_e32 v1, v1, v1
	v_add_f32_e32 v2, v2, v4
	v_fmac_f32_e32 v1, v0, v0
	v_add_f32_e32 v0, v2, v1
	v_add_f32_e32 v0, v3, v0
	v_add_f32_e32 v2, v22, v0
	ds_swizzle_b32 v3, v2 offset:swizzle(SWAP,16)
	v_or_b32_e32 v12, 0x100, v12
	v_pk_mul_f32 v[10:11], v[166:167], v[6:7]
	v_lshl_add_u64 v[0:1], s[44:45], 0, v[12:13]
	v_cvt_pk_bf16_f32 v8, v8, v9
	v_cvt_pk_bf16_f32 v9, v10, v11
	v_cvt_pk_bf16_f32 v10, v18, v19
	v_cvt_pk_bf16_f32 v11, v14, v15
	global_store_dwordx4 v[0:1], v[8:11], off nt
	s_waitcnt lgkmcnt(0)
	v_add_f32_e32 v0, v2, v3
	v_mov_b32_e32 v1, v0
	s_nop 1
	v_permlane32_swap_b32_e32 v0, v1
	s_and_saveexec_b64 s[6:7], s[2:3]
	s_cbranch_execz .LBB0_849
	v_lshl_add_u64 v[2:3], v[16:17], 2, s[10:11]
	v_add_f32_e32 v0, v0, v1
	global_atomic_add_f32 v[2:3], v0, off
